# first K-iteration peeled (C=0 MFMAs, no accumulator zeroing) in the remaining four GEMM loops as well
# speedup vs baseline: 1.0033x; 1.0033x over previous
.LBB0_611:
	v_mov_b32_e32 v127, 0
	s_and_b64 vcc, exec, s[0:1]
	v_mov_b32_e32 v126, v127
	v_mov_b32_e32 v125, v127
	v_mov_b32_e32 v124, v127
	v_mov_b32_e32 v123, v127
	v_mov_b32_e32 v122, v127
	v_mov_b32_e32 v121, v127
	v_mov_b32_e32 v120, v127
	v_mov_b32_e32 v111, v127
	v_mov_b32_e32 v110, v127
	v_mov_b32_e32 v109, v127
	v_mov_b32_e32 v108, v127
	v_mov_b32_e32 v107, v127
	v_mov_b32_e32 v106, v127
	v_mov_b32_e32 v105, v127
	v_mov_b32_e32 v104, v127
	v_mov_b32_e32 v95, v127
	v_mov_b32_e32 v94, v127
	v_mov_b32_e32 v93, v127
	v_mov_b32_e32 v92, v127
	v_mov_b32_e32 v91, v127
	v_mov_b32_e32 v90, v127
	v_mov_b32_e32 v89, v127
	v_mov_b32_e32 v88, v127
	v_mov_b32_e32 v79, v127
	v_mov_b32_e32 v78, v127
	v_mov_b32_e32 v77, v127
	v_mov_b32_e32 v76, v127
	v_mov_b32_e32 v75, v127
	v_mov_b32_e32 v74, v127
	v_mov_b32_e32 v73, v127
	v_mov_b32_e32 v72, v127
	v_mov_b32_e32 v119, v127
	v_mov_b32_e32 v118, v127
	v_mov_b32_e32 v117, v127
	v_mov_b32_e32 v116, v127
	v_mov_b32_e32 v115, v127
	v_mov_b32_e32 v114, v127
	v_mov_b32_e32 v113, v127
	v_mov_b32_e32 v112, v127
	v_mov_b32_e32 v103, v127
	v_mov_b32_e32 v102, v127
	v_mov_b32_e32 v101, v127
	v_mov_b32_e32 v100, v127
	v_mov_b32_e32 v99, v127
	v_mov_b32_e32 v98, v127
	v_mov_b32_e32 v97, v127
	v_mov_b32_e32 v96, v127
	v_mov_b32_e32 v87, v127
	v_mov_b32_e32 v86, v127
	v_mov_b32_e32 v85, v127
	v_mov_b32_e32 v84, v127
	v_mov_b32_e32 v83, v127
	v_mov_b32_e32 v82, v127
	v_mov_b32_e32 v81, v127
	v_mov_b32_e32 v80, v127
	v_mov_b32_e32 v71, v127
	v_mov_b32_e32 v70, v127
	v_mov_b32_e32 v69, v127
	v_mov_b32_e32 v68, v127
	v_mov_b32_e32 v67, v127
	v_mov_b32_e32 v66, v127
	v_mov_b32_e32 v65, v127
	v_mov_b32_e32 v64, v127
	v_mov_b32_e32 v63, v127
	v_mov_b32_e32 v62, v127
	v_mov_b32_e32 v61, v127
	v_mov_b32_e32 v60, v127
	v_mov_b32_e32 v59, v127
	v_mov_b32_e32 v58, v127
	v_mov_b32_e32 v57, v127
	v_mov_b32_e32 v56, v127
	v_mov_b32_e32 v47, v127
	v_mov_b32_e32 v46, v127
	v_mov_b32_e32 v45, v127
	v_mov_b32_e32 v44, v127
	v_mov_b32_e32 v43, v127
	v_mov_b32_e32 v42, v127
	v_mov_b32_e32 v41, v127
	v_mov_b32_e32 v40, v127
	v_mov_b32_e32 v31, v127
	v_mov_b32_e32 v30, v127
	v_mov_b32_e32 v29, v127
	v_mov_b32_e32 v28, v127
	v_mov_b32_e32 v27, v127
	v_mov_b32_e32 v26, v127
	v_mov_b32_e32 v25, v127
	v_mov_b32_e32 v24, v127
	v_mov_b32_e32 v15, v127
	v_mov_b32_e32 v14, v127
	v_mov_b32_e32 v13, v127
	v_mov_b32_e32 v12, v127
	v_mov_b32_e32 v11, v127
	v_mov_b32_e32 v10, v127
	v_mov_b32_e32 v9, v127
	v_mov_b32_e32 v8, v127
	v_mov_b32_e32 v55, v127
	v_mov_b32_e32 v54, v127
	v_mov_b32_e32 v53, v127
	v_mov_b32_e32 v52, v127
	v_mov_b32_e32 v51, v127
	v_mov_b32_e32 v50, v127
	v_mov_b32_e32 v49, v127
	v_mov_b32_e32 v48, v127
	v_mov_b32_e32 v39, v127
	v_mov_b32_e32 v38, v127
	v_mov_b32_e32 v37, v127
	v_mov_b32_e32 v36, v127
	v_mov_b32_e32 v35, v127
	v_mov_b32_e32 v34, v127
	v_mov_b32_e32 v33, v127
	v_mov_b32_e32 v32, v127
	v_mov_b32_e32 v23, v127
	v_mov_b32_e32 v22, v127
	v_mov_b32_e32 v21, v127
	v_mov_b32_e32 v20, v127
	v_mov_b32_e32 v19, v127
	v_mov_b32_e32 v18, v127
	v_mov_b32_e32 v17, v127
	v_mov_b32_e32 v16, v127
	v_mov_b32_e32 v7, v127
	v_mov_b32_e32 v6, v127
	v_mov_b32_e32 v5, v127
	v_mov_b32_e32 v4, v127
	v_mov_b32_e32 v3, v127
	v_mov_b32_e32 v2, v127
	v_mov_b32_e32 v1, v127
	v_mov_b32_e32 v0, v127
	s_cbranch_vccnz .LBB0_614
	s_add_u32 s88, s88, 0x80
	s_addc_u32 s89, s89, 0
	s_add_u32 s78, s90, 0x100
	s_addc_u32 s79, s91, 0
	s_mov_b32 s80, 0
	ds_read_b128 v[152:155], v148
	ds_read_b128 v[156:159], v148 offset:1024
	ds_read_b128 v[160:163], v148 offset:2048
	ds_read_b128 v[164:167], v148 offset:3072
	ds_read_b128 v[168:171], v149
	ds_read_b128 v[172:175], v149 offset:1024
	ds_read_b128 v[176:179], v149 offset:2048
	ds_read_b128 v[180:183], v149 offset:3072
	s_add_i32 s81, s80, 2
	s_add_u32 s48, s88, 0x80
	s_addc_u32 s49, s89, 0
	s_cmp_eq_u32 s61, s80
	s_cselect_b32 s91, s5, s49
	s_cselect_b32 s90, s4, s48
	s_cselect_b32 s93, s87, s79
	s_cselect_b32 s92, s86, s78
	s_mov_b32 m0, s70
	v_lshl_add_u64 v[222:223], s[88:89], 0, v[138:139]
	ds_read_b128 v[184:187], v150
	ds_read_b128 v[188:191], v150 offset:1024
	ds_read_b128 v[192:195], v150 offset:2048
	ds_read_b128 v[202:205], v150 offset:3072
	ds_read_b128 v[206:209], v150 offset:4096
	ds_read_b128 v[210:213], v150 offset:5120
	ds_read_b128 v[214:217], v150 offset:6144
	ds_read_b128 v[218:221], v150 offset:7168
	global_load_lds_dwordx4 v[222:223], off
	v_lshl_add_u64 v[222:223], s[88:89], 0, v[140:141]
	s_mov_b32 m0, s71
	s_nop 0
	global_load_lds_dwordx4 v[222:223], off
	s_waitcnt vmcnt(8)
	s_waitcnt lgkmcnt(0)
	s_barrier
	s_setprio 1
	s_waitcnt lgkmcnt(0)
	v_mfma_f32_16x16x32_bf16 v[124:127], v[152:155], v[184:187], 0
	v_mfma_f32_16x16x32_bf16 v[120:123], v[160:163], v[184:187], 0
	v_mfma_f32_16x16x32_bf16 v[108:111], v[152:155], v[192:195], 0
	v_mfma_f32_16x16x32_bf16 v[104:107], v[160:163], v[192:195], 0
	v_mfma_f32_16x16x32_bf16 v[92:95], v[152:155], v[206:209], 0
	v_mfma_f32_16x16x32_bf16 v[88:91], v[160:163], v[206:209], 0
	v_mfma_f32_16x16x32_bf16 v[76:79], v[152:155], v[214:217], 0
	v_mfma_f32_16x16x32_bf16 v[72:75], v[160:163], v[214:217], 0
	v_mfma_f32_16x16x32_bf16 v[124:127], v[156:159], v[188:191], v[124:127]
	v_mfma_f32_16x16x32_bf16 v[120:123], v[164:167], v[188:191], v[120:123]
	v_mfma_f32_16x16x32_bf16 v[108:111], v[156:159], v[202:205], v[108:111]
	v_mfma_f32_16x16x32_bf16 v[104:107], v[164:167], v[202:205], v[104:107]
	v_mfma_f32_16x16x32_bf16 v[92:95], v[156:159], v[210:213], v[92:95]
	v_mfma_f32_16x16x32_bf16 v[88:91], v[164:167], v[210:213], v[88:91]
	v_mfma_f32_16x16x32_bf16 v[76:79], v[156:159], v[218:221], v[76:79]
	v_mfma_f32_16x16x32_bf16 v[72:75], v[164:167], v[218:221], v[72:75]
	s_setprio 0
	s_setprio 1
	v_mfma_f32_16x16x32_bf16 v[116:119], v[168:171], v[184:187], 0
	v_mfma_f32_16x16x32_bf16 v[112:115], v[176:179], v[184:187], 0
	v_mfma_f32_16x16x32_bf16 v[100:103], v[168:171], v[192:195], 0
	v_mfma_f32_16x16x32_bf16 v[96:99], v[176:179], v[192:195], 0
	v_mfma_f32_16x16x32_bf16 v[84:87], v[168:171], v[206:209], 0
	v_mfma_f32_16x16x32_bf16 v[80:83], v[176:179], v[206:209], 0
	v_mfma_f32_16x16x32_bf16 v[68:71], v[168:171], v[214:217], 0
	v_mfma_f32_16x16x32_bf16 v[64:67], v[176:179], v[214:217], 0
	v_mfma_f32_16x16x32_bf16 v[116:119], v[172:175], v[188:191], v[116:119]
	v_mfma_f32_16x16x32_bf16 v[112:115], v[180:183], v[188:191], v[112:115]
	v_mfma_f32_16x16x32_bf16 v[100:103], v[172:175], v[202:205], v[100:103]
	v_mfma_f32_16x16x32_bf16 v[96:99], v[180:183], v[202:205], v[96:99]
	v_mfma_f32_16x16x32_bf16 v[84:87], v[172:175], v[210:213], v[84:87]
	v_mfma_f32_16x16x32_bf16 v[80:83], v[180:183], v[210:213], v[80:83]
	v_mfma_f32_16x16x32_bf16 v[68:71], v[172:175], v[218:221], v[68:71]
	v_mfma_f32_16x16x32_bf16 v[64:67], v[180:183], v[218:221], v[64:67]
	s_setprio 0
	s_barrier
	s_mov_b32 m0, s72
	v_lshl_add_u64 v[222:223], s[92:93], 0, v[132:133]
	ds_read_b128 v[184:187], v150 offset:16384
	ds_read_b128 v[188:191], v150 offset:17408
	ds_read_b128 v[192:195], v150 offset:18432
	ds_read_b128 v[202:205], v150 offset:19456
	ds_read_b128 v[206:209], v150 offset:20480
	ds_read_b128 v[210:213], v150 offset:21504
	ds_read_b128 v[214:217], v150 offset:22528
	ds_read_b128 v[218:221], v150 offset:23552
	global_load_lds_dwordx4 v[222:223], off
	s_add_i32 m0, s72, 0x2000
	v_lshl_add_u64 v[224:225], s[92:93], 0, v[128:129]
	s_add_u32 s92, s92, s10
	s_addc_u32 s93, s93, s11
	s_add_i32 s48, s64, s8
	global_load_lds_dwordx4 v[224:225], off
	v_lshl_add_u64 v[226:227], s[92:93], 0, v[132:133]
	s_mov_b32 m0, s48
	v_lshl_add_u64 v[228:229], s[92:93], 0, v[128:129]
	global_load_lds_dwordx4 v[226:227], off
	s_add_i32 m0, s48, 0x2000
	v_lshl_add_u64 v[230:231], s[90:91], 0, v[134:135]
	global_load_lds_dwordx4 v[228:229], off
	s_mov_b32 m0, s3
	v_lshl_add_u64 v[232:233], s[90:91], 0, v[130:131]
	global_load_lds_dwordx4 v[230:231], off
	s_mov_b32 m0, s14
	s_nop 0
	global_load_lds_dwordx4 v[232:233], off
	s_waitcnt vmcnt(8)
	s_waitcnt lgkmcnt(0)
	s_barrier
	s_setprio 1
	s_waitcnt lgkmcnt(0)
	v_mfma_f32_16x16x32_bf16 v[60:63], v[152:155], v[184:187], 0
	v_mfma_f32_16x16x32_bf16 v[56:59], v[160:163], v[184:187], 0
	v_mfma_f32_16x16x32_bf16 v[44:47], v[152:155], v[192:195], 0
	v_mfma_f32_16x16x32_bf16 v[40:43], v[160:163], v[192:195], 0
	v_mfma_f32_16x16x32_bf16 v[28:31], v[152:155], v[206:209], 0
	v_mfma_f32_16x16x32_bf16 v[24:27], v[160:163], v[206:209], 0
	v_mfma_f32_16x16x32_bf16 v[12:15], v[152:155], v[214:217], 0
	v_mfma_f32_16x16x32_bf16 v[8:11], v[160:163], v[214:217], 0
	v_mfma_f32_16x16x32_bf16 v[60:63], v[156:159], v[188:191], v[60:63]
	v_mfma_f32_16x16x32_bf16 v[56:59], v[164:167], v[188:191], v[56:59]
	v_mfma_f32_16x16x32_bf16 v[44:47], v[156:159], v[202:205], v[44:47]
	v_mfma_f32_16x16x32_bf16 v[40:43], v[164:167], v[202:205], v[40:43]
	v_mfma_f32_16x16x32_bf16 v[28:31], v[156:159], v[210:213], v[28:31]
	v_mfma_f32_16x16x32_bf16 v[24:27], v[164:167], v[210:213], v[24:27]
	v_mfma_f32_16x16x32_bf16 v[12:15], v[156:159], v[218:221], v[12:15]
	v_mfma_f32_16x16x32_bf16 v[8:11], v[164:167], v[218:221], v[8:11]
	s_setprio 0
	s_setprio 1
	v_mfma_f32_16x16x32_bf16 v[52:55], v[168:171], v[184:187], 0
	v_mfma_f32_16x16x32_bf16 v[48:51], v[176:179], v[184:187], 0
	v_mfma_f32_16x16x32_bf16 v[36:39], v[168:171], v[192:195], 0
	v_mfma_f32_16x16x32_bf16 v[32:35], v[176:179], v[192:195], 0
	v_mfma_f32_16x16x32_bf16 v[20:23], v[168:171], v[206:209], 0
	v_mfma_f32_16x16x32_bf16 v[16:19], v[176:179], v[206:209], 0
	v_mfma_f32_16x16x32_bf16 v[4:7], v[168:171], v[214:217], 0
	v_mfma_f32_16x16x32_bf16 v[0:3], v[176:179], v[214:217], 0
	v_mfma_f32_16x16x32_bf16 v[52:55], v[172:175], v[188:191], v[52:55]
	v_mfma_f32_16x16x32_bf16 v[48:51], v[180:183], v[188:191], v[48:51]
	v_mfma_f32_16x16x32_bf16 v[36:39], v[172:175], v[202:205], v[36:39]
	v_mfma_f32_16x16x32_bf16 v[32:35], v[180:183], v[202:205], v[32:35]
	v_mfma_f32_16x16x32_bf16 v[20:23], v[172:175], v[210:213], v[20:23]
	v_mfma_f32_16x16x32_bf16 v[16:19], v[180:183], v[210:213], v[16:19]
	v_mfma_f32_16x16x32_bf16 v[4:7], v[172:175], v[218:221], v[4:7]
	v_mfma_f32_16x16x32_bf16 v[0:3], v[180:183], v[218:221], v[0:3]
	s_setprio 0
	s_barrier
	s_add_i32 s48, 0, 0x18000
	v_add_u32_e32 v151, s48, v147
	s_add_i32 s49, 0, 0x1c000
	ds_read_b128 v[152:155], v151
	ds_read_b128 v[156:159], v151 offset:1024
	ds_read_b128 v[160:163], v151 offset:2048
	ds_read_b128 v[164:167], v151 offset:3072
	v_add_u32_e32 v151, s49, v147
	ds_read_b128 v[168:171], v151
	ds_read_b128 v[172:175], v151 offset:1024
	ds_read_b128 v[176:179], v151 offset:2048
	ds_read_b128 v[180:183], v151 offset:3072
	s_add_u32 s90, s90, s10
	s_addc_u32 s91, s91, s11
	s_mov_b32 m0, s46
	v_lshl_add_u64 v[234:235], s[90:91], 0, v[134:135]
	ds_read_b128 v[184:187], v150 offset:32768
	ds_read_b128 v[188:191], v150 offset:33792
	ds_read_b128 v[192:195], v150 offset:34816
	ds_read_b128 v[202:205], v150 offset:35840
	ds_read_b128 v[206:209], v150 offset:36864
	ds_read_b128 v[210:213], v150 offset:37888
	ds_read_b128 v[214:217], v150 offset:38912
	ds_read_b128 v[218:221], v150 offset:39936
	global_load_lds_dwordx4 v[234:235], off
	v_lshl_add_u64 v[234:235], s[90:91], 0, v[130:131]
	s_mov_b32 m0, s47
	s_nop 0
	global_load_lds_dwordx4 v[234:235], off
	s_waitcnt vmcnt(8)
	s_waitcnt lgkmcnt(0)
	s_barrier
	s_setprio 1
	s_waitcnt lgkmcnt(0)
	v_mfma_f32_16x16x32_bf16 v[124:127], v[152:155], v[184:187], v[124:127]
	v_mfma_f32_16x16x32_bf16 v[120:123], v[160:163], v[184:187], v[120:123]
	v_mfma_f32_16x16x32_bf16 v[108:111], v[152:155], v[192:195], v[108:111]
	v_mfma_f32_16x16x32_bf16 v[104:107], v[160:163], v[192:195], v[104:107]
	v_mfma_f32_16x16x32_bf16 v[92:95], v[152:155], v[206:209], v[92:95]
	v_mfma_f32_16x16x32_bf16 v[88:91], v[160:163], v[206:209], v[88:91]
	v_mfma_f32_16x16x32_bf16 v[76:79], v[152:155], v[214:217], v[76:79]
	v_mfma_f32_16x16x32_bf16 v[72:75], v[160:163], v[214:217], v[72:75]
	v_mfma_f32_16x16x32_bf16 v[124:127], v[156:159], v[188:191], v[124:127]
	v_mfma_f32_16x16x32_bf16 v[120:123], v[164:167], v[188:191], v[120:123]
	v_mfma_f32_16x16x32_bf16 v[108:111], v[156:159], v[202:205], v[108:111]
	v_mfma_f32_16x16x32_bf16 v[104:107], v[164:167], v[202:205], v[104:107]
	v_mfma_f32_16x16x32_bf16 v[92:95], v[156:159], v[210:213], v[92:95]
	v_mfma_f32_16x16x32_bf16 v[88:91], v[164:167], v[210:213], v[88:91]
	v_mfma_f32_16x16x32_bf16 v[76:79], v[156:159], v[218:221], v[76:79]
	v_mfma_f32_16x16x32_bf16 v[72:75], v[164:167], v[218:221], v[72:75]
	s_setprio 0
	s_setprio 1
	v_mfma_f32_16x16x32_bf16 v[116:119], v[168:171], v[184:187], v[116:119]
	v_mfma_f32_16x16x32_bf16 v[112:115], v[176:179], v[184:187], v[112:115]
	v_mfma_f32_16x16x32_bf16 v[100:103], v[168:171], v[192:195], v[100:103]
	v_mfma_f32_16x16x32_bf16 v[96:99], v[176:179], v[192:195], v[96:99]
	v_mfma_f32_16x16x32_bf16 v[84:87], v[168:171], v[206:209], v[84:87]
	v_mfma_f32_16x16x32_bf16 v[80:83], v[176:179], v[206:209], v[80:83]
	v_mfma_f32_16x16x32_bf16 v[68:71], v[168:171], v[214:217], v[68:71]
	v_mfma_f32_16x16x32_bf16 v[64:67], v[176:179], v[214:217], v[64:67]
	v_mfma_f32_16x16x32_bf16 v[116:119], v[172:175], v[188:191], v[116:119]
	v_mfma_f32_16x16x32_bf16 v[112:115], v[180:183], v[188:191], v[112:115]
	v_mfma_f32_16x16x32_bf16 v[100:103], v[172:175], v[202:205], v[100:103]
	v_mfma_f32_16x16x32_bf16 v[96:99], v[180:183], v[202:205], v[96:99]
	v_mfma_f32_16x16x32_bf16 v[84:87], v[172:175], v[210:213], v[84:87]
	v_mfma_f32_16x16x32_bf16 v[80:83], v[180:183], v[210:213], v[80:83]
	v_mfma_f32_16x16x32_bf16 v[68:71], v[172:175], v[218:221], v[68:71]
	v_mfma_f32_16x16x32_bf16 v[64:67], v[180:183], v[218:221], v[64:67]
	s_setprio 0
	s_barrier
	s_add_i32 s48, s48, s8
	v_lshl_add_u64 v[222:223], v[222:223], 0, s[82:83]
	s_mov_b32 m0, s48
	ds_read_b128 v[184:187], v150 offset:49152
	ds_read_b128 v[188:191], v150 offset:50176
	ds_read_b128 v[192:195], v150 offset:51200
	ds_read_b128 v[202:205], v150 offset:52224
	ds_read_b128 v[206:209], v150 offset:53248
	ds_read_b128 v[210:213], v150 offset:54272
	ds_read_b128 v[214:217], v150 offset:55296
	ds_read_b128 v[218:221], v150 offset:56320
	global_load_lds_dwordx4 v[222:223], off
	v_lshl_add_u64 v[222:223], v[224:225], 0, s[82:83]
	s_add_i32 m0, s48, 0x2000
	s_add_i32 s48, s49, s8
	global_load_lds_dwordx4 v[222:223], off
	v_lshl_add_u64 v[222:223], v[226:227], 0, s[82:83]
	s_mov_b32 m0, s48
	s_nop 0
	global_load_lds_dwordx4 v[222:223], off
	v_lshl_add_u64 v[222:223], v[228:229], 0, s[82:83]
	s_add_i32 m0, s48, 0x2000
	s_nop 0
	global_load_lds_dwordx4 v[222:223], off
	v_lshl_add_u64 v[222:223], v[230:231], 0, s[82:83]
	s_mov_b32 m0, s54
	s_nop 0
	global_load_lds_dwordx4 v[222:223], off
	v_lshl_add_u64 v[222:223], v[232:233], 0, s[82:83]
	s_mov_b32 m0, s55
	s_nop 0
	global_load_lds_dwordx4 v[222:223], off
	s_waitcnt vmcnt(8)
	s_waitcnt lgkmcnt(0)
	s_barrier
	s_setprio 1
	s_waitcnt lgkmcnt(0)
	v_mfma_f32_16x16x32_bf16 v[60:63], v[152:155], v[184:187], v[60:63]
	v_mfma_f32_16x16x32_bf16 v[56:59], v[160:163], v[184:187], v[56:59]
	v_mfma_f32_16x16x32_bf16 v[44:47], v[152:155], v[192:195], v[44:47]
	v_mfma_f32_16x16x32_bf16 v[40:43], v[160:163], v[192:195], v[40:43]
	v_mfma_f32_16x16x32_bf16 v[28:31], v[152:155], v[206:209], v[28:31]
	v_mfma_f32_16x16x32_bf16 v[24:27], v[160:163], v[206:209], v[24:27]
	v_mfma_f32_16x16x32_bf16 v[12:15], v[152:155], v[214:217], v[12:15]
	v_mfma_f32_16x16x32_bf16 v[8:11], v[160:163], v[214:217], v[8:11]
	v_mfma_f32_16x16x32_bf16 v[60:63], v[156:159], v[188:191], v[60:63]
	v_mfma_f32_16x16x32_bf16 v[56:59], v[164:167], v[188:191], v[56:59]
	v_mfma_f32_16x16x32_bf16 v[44:47], v[156:159], v[202:205], v[44:47]
	v_mfma_f32_16x16x32_bf16 v[40:43], v[164:167], v[202:205], v[40:43]
	v_mfma_f32_16x16x32_bf16 v[28:31], v[156:159], v[210:213], v[28:31]
	v_mfma_f32_16x16x32_bf16 v[24:27], v[164:167], v[210:213], v[24:27]
	v_mfma_f32_16x16x32_bf16 v[12:15], v[156:159], v[218:221], v[12:15]
	v_mfma_f32_16x16x32_bf16 v[8:11], v[164:167], v[218:221], v[8:11]
	s_setprio 0
	s_setprio 1
	v_mfma_f32_16x16x32_bf16 v[52:55], v[168:171], v[184:187], v[52:55]
	v_mfma_f32_16x16x32_bf16 v[48:51], v[176:179], v[184:187], v[48:51]
	v_mfma_f32_16x16x32_bf16 v[36:39], v[168:171], v[192:195], v[36:39]
	v_mfma_f32_16x16x32_bf16 v[32:35], v[176:179], v[192:195], v[32:35]
	v_mfma_f32_16x16x32_bf16 v[20:23], v[168:171], v[206:209], v[20:23]
	v_mfma_f32_16x16x32_bf16 v[16:19], v[176:179], v[206:209], v[16:19]
	v_mfma_f32_16x16x32_bf16 v[4:7], v[168:171], v[214:217], v[4:7]
	v_mfma_f32_16x16x32_bf16 v[0:3], v[176:179], v[214:217], v[0:3]
	v_mfma_f32_16x16x32_bf16 v[52:55], v[172:175], v[188:191], v[52:55]
	v_mfma_f32_16x16x32_bf16 v[48:51], v[180:183], v[188:191], v[48:51]
	v_mfma_f32_16x16x32_bf16 v[36:39], v[172:175], v[202:205], v[36:39]
	v_mfma_f32_16x16x32_bf16 v[32:35], v[180:183], v[202:205], v[32:35]
	v_mfma_f32_16x16x32_bf16 v[20:23], v[172:175], v[210:213], v[20:23]
	v_mfma_f32_16x16x32_bf16 v[16:19], v[180:183], v[210:213], v[16:19]
	v_mfma_f32_16x16x32_bf16 v[4:7], v[172:175], v[218:221], v[4:7]
	v_mfma_f32_16x16x32_bf16 v[0:3], v[180:183], v[218:221], v[0:3]
	s_setprio 0
	s_barrier
	s_add_u32 s88, s88, 0x100
	s_addc_u32 s89, s89, 0
	s_add_u32 s78, s78, 0x100
	s_addc_u32 s79, s79, 0
	s_cmp_ge_i32 s81, s53
	s_mov_b32 s80, s81

.LBB0_634:
	v_mov_b32_e32 v127, 0
	s_andn2_b64 vcc, exec, s[84:85]
	v_mov_b32_e32 v126, v127
	v_mov_b32_e32 v125, v127
	v_mov_b32_e32 v124, v127
	v_mov_b32_e32 v123, v127
	v_mov_b32_e32 v122, v127
	v_mov_b32_e32 v121, v127
	v_mov_b32_e32 v120, v127
	v_mov_b32_e32 v111, v127
	v_mov_b32_e32 v110, v127
	v_mov_b32_e32 v109, v127
	v_mov_b32_e32 v108, v127
	v_mov_b32_e32 v107, v127
	v_mov_b32_e32 v106, v127
	v_mov_b32_e32 v105, v127
	v_mov_b32_e32 v104, v127
	v_mov_b32_e32 v95, v127
	v_mov_b32_e32 v94, v127
	v_mov_b32_e32 v93, v127
	v_mov_b32_e32 v92, v127
	v_mov_b32_e32 v91, v127
	v_mov_b32_e32 v90, v127
	v_mov_b32_e32 v89, v127
	v_mov_b32_e32 v88, v127
	v_mov_b32_e32 v79, v127
	v_mov_b32_e32 v78, v127
	v_mov_b32_e32 v77, v127
	v_mov_b32_e32 v76, v127
	v_mov_b32_e32 v75, v127
	v_mov_b32_e32 v74, v127
	v_mov_b32_e32 v73, v127
	v_mov_b32_e32 v72, v127
	v_mov_b32_e32 v119, v127
	v_mov_b32_e32 v118, v127
	v_mov_b32_e32 v117, v127
	v_mov_b32_e32 v116, v127
	v_mov_b32_e32 v115, v127
	v_mov_b32_e32 v114, v127
	v_mov_b32_e32 v113, v127
	v_mov_b32_e32 v112, v127
	v_mov_b32_e32 v103, v127
	v_mov_b32_e32 v102, v127
	v_mov_b32_e32 v101, v127
	v_mov_b32_e32 v100, v127
	v_mov_b32_e32 v99, v127
	v_mov_b32_e32 v98, v127
	v_mov_b32_e32 v97, v127
	v_mov_b32_e32 v96, v127
	v_mov_b32_e32 v87, v127
	v_mov_b32_e32 v86, v127
	v_mov_b32_e32 v85, v127
	v_mov_b32_e32 v84, v127
	v_mov_b32_e32 v83, v127
	v_mov_b32_e32 v82, v127
	v_mov_b32_e32 v81, v127
	v_mov_b32_e32 v80, v127
	v_mov_b32_e32 v71, v127
	v_mov_b32_e32 v70, v127
	v_mov_b32_e32 v69, v127
	v_mov_b32_e32 v68, v127
	v_mov_b32_e32 v67, v127
	v_mov_b32_e32 v66, v127
	v_mov_b32_e32 v65, v127
	v_mov_b32_e32 v64, v127
	v_mov_b32_e32 v63, v127
	v_mov_b32_e32 v62, v127
	v_mov_b32_e32 v61, v127
	v_mov_b32_e32 v60, v127
	v_mov_b32_e32 v59, v127
	v_mov_b32_e32 v58, v127
	v_mov_b32_e32 v57, v127
	v_mov_b32_e32 v56, v127
	v_mov_b32_e32 v47, v127
	v_mov_b32_e32 v46, v127
	v_mov_b32_e32 v45, v127
	v_mov_b32_e32 v44, v127
	v_mov_b32_e32 v43, v127
	v_mov_b32_e32 v42, v127
	v_mov_b32_e32 v41, v127
	v_mov_b32_e32 v40, v127
	v_mov_b32_e32 v31, v127
	v_mov_b32_e32 v30, v127
	v_mov_b32_e32 v29, v127
	v_mov_b32_e32 v28, v127
	v_mov_b32_e32 v27, v127
	v_mov_b32_e32 v26, v127
	v_mov_b32_e32 v25, v127
	v_mov_b32_e32 v24, v127
	v_mov_b32_e32 v15, v127
	v_mov_b32_e32 v14, v127
	v_mov_b32_e32 v13, v127
	v_mov_b32_e32 v12, v127
	v_mov_b32_e32 v11, v127
	v_mov_b32_e32 v10, v127
	v_mov_b32_e32 v9, v127
	v_mov_b32_e32 v8, v127
	v_mov_b32_e32 v55, v127
	v_mov_b32_e32 v54, v127
	v_mov_b32_e32 v53, v127
	v_mov_b32_e32 v52, v127
	v_mov_b32_e32 v51, v127
	v_mov_b32_e32 v50, v127
	v_mov_b32_e32 v49, v127
	v_mov_b32_e32 v48, v127
	v_mov_b32_e32 v39, v127
	v_mov_b32_e32 v38, v127
	v_mov_b32_e32 v37, v127
	v_mov_b32_e32 v36, v127
	v_mov_b32_e32 v35, v127
	v_mov_b32_e32 v34, v127
	v_mov_b32_e32 v33, v127
	v_mov_b32_e32 v32, v127
	v_mov_b32_e32 v23, v127
	v_mov_b32_e32 v22, v127
	v_mov_b32_e32 v21, v127
	v_mov_b32_e32 v20, v127
	v_mov_b32_e32 v19, v127
	v_mov_b32_e32 v18, v127
	v_mov_b32_e32 v17, v127
	v_mov_b32_e32 v16, v127
	v_mov_b32_e32 v7, v127
	v_mov_b32_e32 v6, v127
	v_mov_b32_e32 v5, v127
	v_mov_b32_e32 v4, v127
	v_mov_b32_e32 v3, v127
	v_mov_b32_e32 v2, v127
	v_mov_b32_e32 v1, v127
	v_mov_b32_e32 v0, v127
	s_cbranch_vccnz .LBB0_637
	s_add_u32 s90, s90, 0x80
	s_addc_u32 s91, s91, 0
	s_add_u32 s8, s92, 0x100
	s_addc_u32 s9, s93, 0
	s_mov_b32 s53, 0
	ds_read_b128 v[128:131], v161
	ds_read_b128 v[132:135], v161 offset:1024
	ds_read_b128 v[154:157], v161 offset:2048
	ds_read_b128 v[166:169], v161 offset:3072
	ds_read_b128 v[170:173], v162
	ds_read_b128 v[174:177], v162 offset:1024
	ds_read_b128 v[178:181], v162 offset:2048
	ds_read_b128 v[182:185], v162 offset:3072
	s_add_i32 vcc_lo, s53, 2
	s_add_u32 s48, s90, 0x80
	s_addc_u32 s49, s91, 0
	s_cmp_eq_u32 s81, s53
	s_cselect_b32 s93, s1, s49
	s_cselect_b32 s92, s0, s48
	s_cselect_b32 s49, s89, s9
	s_cselect_b32 s48, s88, s8
	v_lshl_add_u64 v[194:195], s[90:91], 0, v[146:147]
	s_add_i32 m0, s73, 0xc000
	ds_read_b128 v[186:189], v163
	ds_read_b128 v[190:193], v163 offset:1024
	ds_read_b128 v[202:205], v163 offset:2048
	ds_read_b128 v[206:209], v163 offset:3072
	ds_read_b128 v[210:213], v163 offset:4096
	ds_read_b128 v[214:217], v163 offset:5120
	ds_read_b128 v[218:221], v163 offset:6144
	ds_read_b128 v[222:225], v163 offset:7168
	global_load_lds_dwordx4 v[194:195], off
	v_lshl_add_u64 v[194:195], s[90:91], 0, v[148:149]
	s_add_i32 m0, s73, 0xe000
	s_nop 0
	global_load_lds_dwordx4 v[194:195], off
	s_waitcnt vmcnt(8)
	s_waitcnt lgkmcnt(0)
	s_barrier
	s_setprio 1
	s_waitcnt lgkmcnt(0)
	v_mfma_f32_16x16x32_bf16 v[124:127], v[128:131], v[186:189], 0
	v_mfma_f32_16x16x32_bf16 v[120:123], v[154:157], v[186:189], 0
	v_mfma_f32_16x16x32_bf16 v[108:111], v[128:131], v[202:205], 0
	v_mfma_f32_16x16x32_bf16 v[104:107], v[154:157], v[202:205], 0
	v_mfma_f32_16x16x32_bf16 v[92:95], v[128:131], v[210:213], 0
	v_mfma_f32_16x16x32_bf16 v[88:91], v[154:157], v[210:213], 0
	v_mfma_f32_16x16x32_bf16 v[76:79], v[128:131], v[218:221], 0
	v_mfma_f32_16x16x32_bf16 v[72:75], v[154:157], v[218:221], 0
	v_mfma_f32_16x16x32_bf16 v[124:127], v[132:135], v[190:193], v[124:127]
	v_mfma_f32_16x16x32_bf16 v[120:123], v[166:169], v[190:193], v[120:123]
	v_mfma_f32_16x16x32_bf16 v[108:111], v[132:135], v[206:209], v[108:111]
	v_mfma_f32_16x16x32_bf16 v[104:107], v[166:169], v[206:209], v[104:107]
	v_mfma_f32_16x16x32_bf16 v[92:95], v[132:135], v[214:217], v[92:95]
	v_mfma_f32_16x16x32_bf16 v[88:91], v[166:169], v[214:217], v[88:91]
	v_mfma_f32_16x16x32_bf16 v[76:79], v[132:135], v[222:225], v[76:79]
	v_mfma_f32_16x16x32_bf16 v[72:75], v[166:169], v[222:225], v[72:75]
	s_setprio 0
	s_setprio 1
	v_mfma_f32_16x16x32_bf16 v[116:119], v[170:173], v[186:189], 0
	v_mfma_f32_16x16x32_bf16 v[112:115], v[178:181], v[186:189], 0
	v_mfma_f32_16x16x32_bf16 v[100:103], v[170:173], v[202:205], 0
	v_mfma_f32_16x16x32_bf16 v[96:99], v[178:181], v[202:205], 0
	v_mfma_f32_16x16x32_bf16 v[84:87], v[170:173], v[210:213], 0
	v_mfma_f32_16x16x32_bf16 v[80:83], v[178:181], v[210:213], 0
	v_mfma_f32_16x16x32_bf16 v[68:71], v[170:173], v[218:221], 0
	v_mfma_f32_16x16x32_bf16 v[64:67], v[178:181], v[218:221], 0
	v_mfma_f32_16x16x32_bf16 v[116:119], v[174:177], v[190:193], v[116:119]
	v_mfma_f32_16x16x32_bf16 v[112:115], v[182:185], v[190:193], v[112:115]
	v_mfma_f32_16x16x32_bf16 v[100:103], v[174:177], v[206:209], v[100:103]
	v_mfma_f32_16x16x32_bf16 v[96:99], v[182:185], v[206:209], v[96:99]
	v_mfma_f32_16x16x32_bf16 v[84:87], v[174:177], v[214:217], v[84:87]
	v_mfma_f32_16x16x32_bf16 v[80:83], v[182:185], v[214:217], v[80:83]
	v_mfma_f32_16x16x32_bf16 v[68:71], v[174:177], v[222:225], v[68:71]
	v_mfma_f32_16x16x32_bf16 v[64:67], v[182:185], v[222:225], v[64:67]
	s_setprio 0
	s_barrier
	s_add_i32 s53, s3, s65
	v_lshl_add_u64 v[194:195], s[48:49], 0, v[138:139]
	s_mov_b32 m0, s53
	ds_read_b128 v[186:189], v163 offset:16384
	ds_read_b128 v[190:193], v163 offset:17408
	ds_read_b128 v[202:205], v163 offset:18432
	ds_read_b128 v[206:209], v163 offset:19456
	ds_read_b128 v[210:213], v163 offset:20480
	ds_read_b128 v[214:217], v163 offset:21504
	ds_read_b128 v[218:221], v163 offset:22528
	ds_read_b128 v[222:225], v163 offset:23552
	global_load_lds_dwordx4 v[194:195], off
	s_add_i32 m0, s53, 0x2000
	v_lshl_add_u64 v[226:227], s[48:49], 0, v[142:143]
	s_add_u32 s48, s48, s6
	s_addc_u32 s49, s49, s7
	s_add_i32 s53, s54, s65
	global_load_lds_dwordx4 v[226:227], off
	v_lshl_add_u64 v[228:229], s[48:49], 0, v[138:139]
	s_mov_b32 m0, s53
	v_lshl_add_u64 v[230:231], s[48:49], 0, v[142:143]
	global_load_lds_dwordx4 v[228:229], off
	s_add_i32 m0, s53, 0x2000
	v_lshl_add_u64 v[232:233], s[92:93], 0, v[136:137]
	global_load_lds_dwordx4 v[230:231], off
	s_mov_b32 m0, s73
	v_lshl_add_u64 v[234:235], s[92:93], 0, v[140:141]
	global_load_lds_dwordx4 v[232:233], off
	s_mov_b32 m0, s75
	s_nop 0
	global_load_lds_dwordx4 v[234:235], off
	s_waitcnt vmcnt(8)
	s_waitcnt lgkmcnt(0)
	s_barrier
	s_setprio 1
	s_waitcnt lgkmcnt(0)
	v_mfma_f32_16x16x32_bf16 v[60:63], v[128:131], v[186:189], 0
	v_mfma_f32_16x16x32_bf16 v[56:59], v[154:157], v[186:189], 0
	v_mfma_f32_16x16x32_bf16 v[44:47], v[128:131], v[202:205], 0
	v_mfma_f32_16x16x32_bf16 v[40:43], v[154:157], v[202:205], 0
	v_mfma_f32_16x16x32_bf16 v[28:31], v[128:131], v[210:213], 0
	v_mfma_f32_16x16x32_bf16 v[24:27], v[154:157], v[210:213], 0
	v_mfma_f32_16x16x32_bf16 v[12:15], v[128:131], v[218:221], 0
	v_mfma_f32_16x16x32_bf16 v[8:11], v[154:157], v[218:221], 0
	v_mfma_f32_16x16x32_bf16 v[60:63], v[132:135], v[190:193], v[60:63]
	v_mfma_f32_16x16x32_bf16 v[56:59], v[166:169], v[190:193], v[56:59]
	v_mfma_f32_16x16x32_bf16 v[44:47], v[132:135], v[206:209], v[44:47]
	v_mfma_f32_16x16x32_bf16 v[40:43], v[166:169], v[206:209], v[40:43]
	v_mfma_f32_16x16x32_bf16 v[28:31], v[132:135], v[214:217], v[28:31]
	v_mfma_f32_16x16x32_bf16 v[24:27], v[166:169], v[214:217], v[24:27]
	v_mfma_f32_16x16x32_bf16 v[12:15], v[132:135], v[222:225], v[12:15]
	v_mfma_f32_16x16x32_bf16 v[8:11], v[166:169], v[222:225], v[8:11]
	s_setprio 0
	s_setprio 1
	v_mfma_f32_16x16x32_bf16 v[52:55], v[170:173], v[186:189], 0
	v_mfma_f32_16x16x32_bf16 v[48:51], v[178:181], v[186:189], 0
	v_mfma_f32_16x16x32_bf16 v[36:39], v[170:173], v[202:205], 0
	v_mfma_f32_16x16x32_bf16 v[32:35], v[178:181], v[202:205], 0
	v_mfma_f32_16x16x32_bf16 v[20:23], v[170:173], v[210:213], 0
	v_mfma_f32_16x16x32_bf16 v[16:19], v[178:181], v[210:213], 0
	v_mfma_f32_16x16x32_bf16 v[4:7], v[170:173], v[218:221], 0
	v_mfma_f32_16x16x32_bf16 v[0:3], v[178:181], v[218:221], 0
	v_mfma_f32_16x16x32_bf16 v[52:55], v[174:177], v[190:193], v[52:55]
	v_mfma_f32_16x16x32_bf16 v[48:51], v[182:185], v[190:193], v[48:51]
	v_mfma_f32_16x16x32_bf16 v[36:39], v[174:177], v[206:209], v[36:39]
	v_mfma_f32_16x16x32_bf16 v[32:35], v[182:185], v[206:209], v[32:35]
	v_mfma_f32_16x16x32_bf16 v[20:23], v[174:177], v[214:217], v[20:23]
	v_mfma_f32_16x16x32_bf16 v[16:19], v[182:185], v[214:217], v[16:19]
	v_mfma_f32_16x16x32_bf16 v[4:7], v[174:177], v[222:225], v[4:7]
	v_mfma_f32_16x16x32_bf16 v[0:3], v[182:185], v[222:225], v[0:3]
	s_setprio 0
	s_barrier
	s_add_i32 s53, 0, 0x18000
	v_add_u32_e32 v144, s53, v160
	s_add_i32 vcc_hi, 0, 0x1c000
	ds_read_b128 v[128:131], v144
	ds_read_b128 v[132:135], v144 offset:1024
	ds_read_b128 v[154:157], v144 offset:2048
	ds_read_b128 v[166:169], v144 offset:3072
	v_add_u32_e32 v144, vcc_hi, v160
	ds_read_b128 v[170:173], v144
	ds_read_b128 v[174:177], v144 offset:1024
	ds_read_b128 v[178:181], v144 offset:2048
	ds_read_b128 v[182:185], v144 offset:3072
	s_add_u32 s48, s92, s6
	s_addc_u32 s49, s93, s7
	s_mov_b32 m0, s77
	v_lshl_add_u64 v[236:237], s[48:49], 0, v[136:137]
	ds_read_b128 v[186:189], v163 offset:32768
	ds_read_b128 v[190:193], v163 offset:33792
	ds_read_b128 v[202:205], v163 offset:34816
	ds_read_b128 v[206:209], v163 offset:35840
	ds_read_b128 v[210:213], v163 offset:36864
	ds_read_b128 v[214:217], v163 offset:37888
	ds_read_b128 v[218:221], v163 offset:38912
	ds_read_b128 v[222:225], v163 offset:39936
	global_load_lds_dwordx4 v[236:237], off
	v_lshl_add_u64 v[236:237], s[48:49], 0, v[140:141]
	s_mov_b32 m0, s78
	s_nop 0
	global_load_lds_dwordx4 v[236:237], off
	s_waitcnt vmcnt(8)
	s_waitcnt lgkmcnt(0)
	s_barrier
	s_setprio 1
	s_waitcnt lgkmcnt(0)
	v_mfma_f32_16x16x32_bf16 v[124:127], v[128:131], v[186:189], v[124:127]
	v_mfma_f32_16x16x32_bf16 v[120:123], v[154:157], v[186:189], v[120:123]
	v_mfma_f32_16x16x32_bf16 v[108:111], v[128:131], v[202:205], v[108:111]
	v_mfma_f32_16x16x32_bf16 v[104:107], v[154:157], v[202:205], v[104:107]
	v_mfma_f32_16x16x32_bf16 v[92:95], v[128:131], v[210:213], v[92:95]
	v_mfma_f32_16x16x32_bf16 v[88:91], v[154:157], v[210:213], v[88:91]
	v_mfma_f32_16x16x32_bf16 v[76:79], v[128:131], v[218:221], v[76:79]
	v_mfma_f32_16x16x32_bf16 v[72:75], v[154:157], v[218:221], v[72:75]
	v_mfma_f32_16x16x32_bf16 v[124:127], v[132:135], v[190:193], v[124:127]
	v_mfma_f32_16x16x32_bf16 v[120:123], v[166:169], v[190:193], v[120:123]
	v_mfma_f32_16x16x32_bf16 v[108:111], v[132:135], v[206:209], v[108:111]
	v_mfma_f32_16x16x32_bf16 v[104:107], v[166:169], v[206:209], v[104:107]
	v_mfma_f32_16x16x32_bf16 v[92:95], v[132:135], v[214:217], v[92:95]
	v_mfma_f32_16x16x32_bf16 v[88:91], v[166:169], v[214:217], v[88:91]
	v_mfma_f32_16x16x32_bf16 v[76:79], v[132:135], v[222:225], v[76:79]
	v_mfma_f32_16x16x32_bf16 v[72:75], v[166:169], v[222:225], v[72:75]
	s_setprio 0
	s_setprio 1
	v_mfma_f32_16x16x32_bf16 v[116:119], v[170:173], v[186:189], v[116:119]
	v_mfma_f32_16x16x32_bf16 v[112:115], v[178:181], v[186:189], v[112:115]
	v_mfma_f32_16x16x32_bf16 v[100:103], v[170:173], v[202:205], v[100:103]
	v_mfma_f32_16x16x32_bf16 v[96:99], v[178:181], v[202:205], v[96:99]
	v_mfma_f32_16x16x32_bf16 v[84:87], v[170:173], v[210:213], v[84:87]
	v_mfma_f32_16x16x32_bf16 v[80:83], v[178:181], v[210:213], v[80:83]
	v_mfma_f32_16x16x32_bf16 v[68:71], v[170:173], v[218:221], v[68:71]
	v_mfma_f32_16x16x32_bf16 v[64:67], v[178:181], v[218:221], v[64:67]
	v_mfma_f32_16x16x32_bf16 v[116:119], v[174:177], v[190:193], v[116:119]
	v_mfma_f32_16x16x32_bf16 v[112:115], v[182:185], v[190:193], v[112:115]
	v_mfma_f32_16x16x32_bf16 v[100:103], v[174:177], v[206:209], v[100:103]
	v_mfma_f32_16x16x32_bf16 v[96:99], v[182:185], v[206:209], v[96:99]
	v_mfma_f32_16x16x32_bf16 v[84:87], v[174:177], v[214:217], v[84:87]
	v_mfma_f32_16x16x32_bf16 v[80:83], v[182:185], v[214:217], v[80:83]
	v_mfma_f32_16x16x32_bf16 v[68:71], v[174:177], v[222:225], v[68:71]
	v_mfma_f32_16x16x32_bf16 v[64:67], v[182:185], v[222:225], v[64:67]
	s_setprio 0
	s_barrier
	s_add_i32 s48, s53, s65
	v_lshl_add_u64 v[194:195], v[194:195], 0, s[82:83]
	s_mov_b32 m0, s48
	ds_read_b128 v[186:189], v163 offset:49152
	ds_read_b128 v[190:193], v163 offset:50176
	ds_read_b128 v[202:205], v163 offset:51200
	ds_read_b128 v[206:209], v163 offset:52224
	ds_read_b128 v[210:213], v163 offset:53248
	ds_read_b128 v[214:217], v163 offset:54272
	ds_read_b128 v[218:221], v163 offset:55296
	ds_read_b128 v[222:225], v163 offset:56320
	global_load_lds_dwordx4 v[194:195], off
	v_lshl_add_u64 v[194:195], v[226:227], 0, s[82:83]
	s_add_i32 m0, s48, 0x2000
	s_add_i32 s48, vcc_hi, s65
	global_load_lds_dwordx4 v[194:195], off
	v_lshl_add_u64 v[194:195], v[228:229], 0, s[82:83]
	s_mov_b32 m0, s48
	s_nop 0
	global_load_lds_dwordx4 v[194:195], off
	v_lshl_add_u64 v[194:195], v[230:231], 0, s[82:83]
	s_add_i32 m0, s48, 0x2000
	s_nop 0
	global_load_lds_dwordx4 v[194:195], off
	v_lshl_add_u64 v[194:195], v[232:233], 0, s[82:83]
	s_mov_b32 m0, s96
	s_nop 0
	global_load_lds_dwordx4 v[194:195], off
	v_lshl_add_u64 v[194:195], v[234:235], 0, s[82:83]
	s_mov_b32 m0, s97
	s_nop 0
	global_load_lds_dwordx4 v[194:195], off
	s_waitcnt vmcnt(8)
	s_waitcnt lgkmcnt(0)
	s_barrier
	s_setprio 1
	s_waitcnt lgkmcnt(0)
	v_mfma_f32_16x16x32_bf16 v[60:63], v[128:131], v[186:189], v[60:63]
	v_mfma_f32_16x16x32_bf16 v[56:59], v[154:157], v[186:189], v[56:59]
	v_mfma_f32_16x16x32_bf16 v[44:47], v[128:131], v[202:205], v[44:47]
	v_mfma_f32_16x16x32_bf16 v[40:43], v[154:157], v[202:205], v[40:43]
	v_mfma_f32_16x16x32_bf16 v[28:31], v[128:131], v[210:213], v[28:31]
	v_mfma_f32_16x16x32_bf16 v[24:27], v[154:157], v[210:213], v[24:27]
	v_mfma_f32_16x16x32_bf16 v[12:15], v[128:131], v[218:221], v[12:15]
	v_mfma_f32_16x16x32_bf16 v[8:11], v[154:157], v[218:221], v[8:11]
	v_mfma_f32_16x16x32_bf16 v[60:63], v[132:135], v[190:193], v[60:63]
	v_mfma_f32_16x16x32_bf16 v[56:59], v[166:169], v[190:193], v[56:59]
	v_mfma_f32_16x16x32_bf16 v[44:47], v[132:135], v[206:209], v[44:47]
	v_mfma_f32_16x16x32_bf16 v[40:43], v[166:169], v[206:209], v[40:43]
	v_mfma_f32_16x16x32_bf16 v[28:31], v[132:135], v[214:217], v[28:31]
	v_mfma_f32_16x16x32_bf16 v[24:27], v[166:169], v[214:217], v[24:27]
	v_mfma_f32_16x16x32_bf16 v[12:15], v[132:135], v[222:225], v[12:15]
	v_mfma_f32_16x16x32_bf16 v[8:11], v[166:169], v[222:225], v[8:11]
	s_setprio 0
	s_setprio 1
	v_mfma_f32_16x16x32_bf16 v[52:55], v[170:173], v[186:189], v[52:55]
	v_mfma_f32_16x16x32_bf16 v[48:51], v[178:181], v[186:189], v[48:51]
	v_mfma_f32_16x16x32_bf16 v[36:39], v[170:173], v[202:205], v[36:39]
	v_mfma_f32_16x16x32_bf16 v[32:35], v[178:181], v[202:205], v[32:35]
	v_mfma_f32_16x16x32_bf16 v[20:23], v[170:173], v[210:213], v[20:23]
	v_mfma_f32_16x16x32_bf16 v[16:19], v[178:181], v[210:213], v[16:19]
	v_mfma_f32_16x16x32_bf16 v[4:7], v[170:173], v[218:221], v[4:7]
	v_mfma_f32_16x16x32_bf16 v[0:3], v[178:181], v[218:221], v[0:3]
	v_mfma_f32_16x16x32_bf16 v[52:55], v[174:177], v[190:193], v[52:55]
	v_mfma_f32_16x16x32_bf16 v[48:51], v[182:185], v[190:193], v[48:51]
	v_mfma_f32_16x16x32_bf16 v[36:39], v[174:177], v[206:209], v[36:39]
	v_mfma_f32_16x16x32_bf16 v[32:35], v[182:185], v[206:209], v[32:35]
	v_mfma_f32_16x16x32_bf16 v[20:23], v[174:177], v[214:217], v[20:23]
	v_mfma_f32_16x16x32_bf16 v[16:19], v[182:185], v[214:217], v[16:19]
	v_mfma_f32_16x16x32_bf16 v[4:7], v[174:177], v[222:225], v[4:7]
	v_mfma_f32_16x16x32_bf16 v[0:3], v[182:185], v[222:225], v[0:3]
	s_setprio 0
	s_barrier
	s_add_u32 s90, s90, 0x100
	s_addc_u32 s91, s91, 0
	s_add_u32 s8, s8, 0x100
	s_addc_u32 s9, s9, 0
	s_cmp_ge_i32 vcc_lo, s70
	s_mov_b32 s53, vcc_lo

.LBB0_725:
	v_mov_b32_e32 v127, 0
	s_and_b64 vcc, exec, s[0:1]
	v_mov_b32_e32 v126, v127
	v_mov_b32_e32 v125, v127
	v_mov_b32_e32 v124, v127
	v_mov_b32_e32 v123, v127
	v_mov_b32_e32 v122, v127
	v_mov_b32_e32 v121, v127
	v_mov_b32_e32 v120, v127
	v_mov_b32_e32 v111, v127
	v_mov_b32_e32 v110, v127
	v_mov_b32_e32 v109, v127
	v_mov_b32_e32 v108, v127
	v_mov_b32_e32 v107, v127
	v_mov_b32_e32 v106, v127
	v_mov_b32_e32 v105, v127
	v_mov_b32_e32 v104, v127
	v_mov_b32_e32 v95, v127
	v_mov_b32_e32 v94, v127
	v_mov_b32_e32 v93, v127
	v_mov_b32_e32 v92, v127
	v_mov_b32_e32 v91, v127
	v_mov_b32_e32 v90, v127
	v_mov_b32_e32 v89, v127
	v_mov_b32_e32 v88, v127
	v_mov_b32_e32 v79, v127
	v_mov_b32_e32 v78, v127
	v_mov_b32_e32 v77, v127
	v_mov_b32_e32 v76, v127
	v_mov_b32_e32 v75, v127
	v_mov_b32_e32 v74, v127
	v_mov_b32_e32 v73, v127
	v_mov_b32_e32 v72, v127
	v_mov_b32_e32 v119, v127
	v_mov_b32_e32 v118, v127
	v_mov_b32_e32 v117, v127
	v_mov_b32_e32 v116, v127
	v_mov_b32_e32 v115, v127
	v_mov_b32_e32 v114, v127
	v_mov_b32_e32 v113, v127
	v_mov_b32_e32 v112, v127
	v_mov_b32_e32 v103, v127
	v_mov_b32_e32 v102, v127
	v_mov_b32_e32 v101, v127
	v_mov_b32_e32 v100, v127
	v_mov_b32_e32 v99, v127
	v_mov_b32_e32 v98, v127
	v_mov_b32_e32 v97, v127
	v_mov_b32_e32 v96, v127
	v_mov_b32_e32 v87, v127
	v_mov_b32_e32 v86, v127
	v_mov_b32_e32 v85, v127
	v_mov_b32_e32 v84, v127
	v_mov_b32_e32 v83, v127
	v_mov_b32_e32 v82, v127
	v_mov_b32_e32 v81, v127
	v_mov_b32_e32 v80, v127
	v_mov_b32_e32 v71, v127
	v_mov_b32_e32 v70, v127
	v_mov_b32_e32 v69, v127
	v_mov_b32_e32 v68, v127
	v_mov_b32_e32 v67, v127
	v_mov_b32_e32 v66, v127
	v_mov_b32_e32 v65, v127
	v_mov_b32_e32 v64, v127
	v_mov_b32_e32 v63, v127
	v_mov_b32_e32 v62, v127
	v_mov_b32_e32 v61, v127
	v_mov_b32_e32 v60, v127
	v_mov_b32_e32 v59, v127
	v_mov_b32_e32 v58, v127
	v_mov_b32_e32 v57, v127
	v_mov_b32_e32 v56, v127
	v_mov_b32_e32 v47, v127
	v_mov_b32_e32 v46, v127
	v_mov_b32_e32 v45, v127
	v_mov_b32_e32 v44, v127
	v_mov_b32_e32 v43, v127
	v_mov_b32_e32 v42, v127
	v_mov_b32_e32 v41, v127
	v_mov_b32_e32 v40, v127
	v_mov_b32_e32 v31, v127
	v_mov_b32_e32 v30, v127
	v_mov_b32_e32 v29, v127
	v_mov_b32_e32 v28, v127
	v_mov_b32_e32 v27, v127
	v_mov_b32_e32 v26, v127
	v_mov_b32_e32 v25, v127
	v_mov_b32_e32 v24, v127
	v_mov_b32_e32 v15, v127
	v_mov_b32_e32 v14, v127
	v_mov_b32_e32 v13, v127
	v_mov_b32_e32 v12, v127
	v_mov_b32_e32 v11, v127
	v_mov_b32_e32 v10, v127
	v_mov_b32_e32 v9, v127
	v_mov_b32_e32 v8, v127
	v_mov_b32_e32 v55, v127
	v_mov_b32_e32 v54, v127
	v_mov_b32_e32 v53, v127
	v_mov_b32_e32 v52, v127
	v_mov_b32_e32 v51, v127
	v_mov_b32_e32 v50, v127
	v_mov_b32_e32 v49, v127
	v_mov_b32_e32 v48, v127
	v_mov_b32_e32 v39, v127
	v_mov_b32_e32 v38, v127
	v_mov_b32_e32 v37, v127
	v_mov_b32_e32 v36, v127
	v_mov_b32_e32 v35, v127
	v_mov_b32_e32 v34, v127
	v_mov_b32_e32 v33, v127
	v_mov_b32_e32 v32, v127
	v_mov_b32_e32 v23, v127
	v_mov_b32_e32 v22, v127
	v_mov_b32_e32 v21, v127
	v_mov_b32_e32 v20, v127
	v_mov_b32_e32 v19, v127
	v_mov_b32_e32 v18, v127
	v_mov_b32_e32 v17, v127
	v_mov_b32_e32 v16, v127
	v_mov_b32_e32 v7, v127
	v_mov_b32_e32 v6, v127
	v_mov_b32_e32 v5, v127
	v_mov_b32_e32 v4, v127
	v_mov_b32_e32 v3, v127
	v_mov_b32_e32 v2, v127
	v_mov_b32_e32 v1, v127
	v_mov_b32_e32 v0, v127
	s_cbranch_vccnz .LBB0_728
	s_add_u32 s86, s86, 0x80
	s_addc_u32 s87, s87, 0
	s_add_u32 s90, s88, 0x100
	s_addc_u32 s91, s89, 0
	s_mov_b32 s88, 0
	ds_read_b128 v[148:151], v155
	ds_read_b128 v[160:163], v155 offset:1024
	ds_read_b128 v[164:167], v155 offset:2048
	ds_read_b128 v[168:171], v155 offset:3072
	ds_read_b128 v[172:175], v156
	ds_read_b128 v[176:179], v156 offset:1024
	ds_read_b128 v[180:183], v156 offset:2048
	ds_read_b128 v[184:187], v156 offset:3072
	s_add_i32 s92, s88, 2
	s_add_u32 s48, s86, 0x80
	s_addc_u32 s49, s87, 0
	s_cmp_eq_u32 s73, s88
	s_cselect_b32 s88, s4, s48
	s_cselect_b32 s89, s5, s49
	s_cselect_b32 s49, s85, s91
	s_cselect_b32 s48, s84, s90
	s_mov_b32 m0, s79
	v_lshl_add_u64 v[226:227], s[86:87], 0, v[140:141]
	ds_read_b128 v[188:191], v157
	ds_read_b128 v[192:195], v157 offset:1024
	ds_read_b128 v[202:205], v157 offset:2048
	ds_read_b128 v[206:209], v157 offset:3072
	ds_read_b128 v[210:213], v157 offset:4096
	ds_read_b128 v[214:217], v157 offset:5120
	ds_read_b128 v[218:221], v157 offset:6144
	ds_read_b128 v[222:225], v157 offset:7168
	global_load_lds_dwordx4 v[226:227], off
	v_lshl_add_u64 v[226:227], s[86:87], 0, v[142:143]
	s_add_i32 m0, s52, 0xe000
	s_nop 0
	global_load_lds_dwordx4 v[226:227], off
	s_waitcnt vmcnt(8)
	s_waitcnt lgkmcnt(0)
	s_barrier
	s_setprio 1
	s_waitcnt lgkmcnt(0)
	v_mfma_f32_16x16x32_bf16 v[124:127], v[148:151], v[188:191], 0
	v_mfma_f32_16x16x32_bf16 v[120:123], v[164:167], v[188:191], 0
	v_mfma_f32_16x16x32_bf16 v[108:111], v[148:151], v[202:205], 0
	v_mfma_f32_16x16x32_bf16 v[104:107], v[164:167], v[202:205], 0
	v_mfma_f32_16x16x32_bf16 v[92:95], v[148:151], v[210:213], 0
	v_mfma_f32_16x16x32_bf16 v[88:91], v[164:167], v[210:213], 0
	v_mfma_f32_16x16x32_bf16 v[76:79], v[148:151], v[218:221], 0
	v_mfma_f32_16x16x32_bf16 v[72:75], v[164:167], v[218:221], 0
	v_mfma_f32_16x16x32_bf16 v[124:127], v[160:163], v[192:195], v[124:127]
	v_mfma_f32_16x16x32_bf16 v[120:123], v[168:171], v[192:195], v[120:123]
	v_mfma_f32_16x16x32_bf16 v[108:111], v[160:163], v[206:209], v[108:111]
	v_mfma_f32_16x16x32_bf16 v[104:107], v[168:171], v[206:209], v[104:107]
	v_mfma_f32_16x16x32_bf16 v[92:95], v[160:163], v[214:217], v[92:95]
	v_mfma_f32_16x16x32_bf16 v[88:91], v[168:171], v[214:217], v[88:91]
	v_mfma_f32_16x16x32_bf16 v[76:79], v[160:163], v[222:225], v[76:79]
	v_mfma_f32_16x16x32_bf16 v[72:75], v[168:171], v[222:225], v[72:75]
	s_setprio 0
	s_setprio 1
	v_mfma_f32_16x16x32_bf16 v[116:119], v[172:175], v[188:191], 0
	v_mfma_f32_16x16x32_bf16 v[112:115], v[180:183], v[188:191], 0
	v_mfma_f32_16x16x32_bf16 v[100:103], v[172:175], v[202:205], 0
	v_mfma_f32_16x16x32_bf16 v[96:99], v[180:183], v[202:205], 0
	v_mfma_f32_16x16x32_bf16 v[84:87], v[172:175], v[210:213], 0
	v_mfma_f32_16x16x32_bf16 v[80:83], v[180:183], v[210:213], 0
	v_mfma_f32_16x16x32_bf16 v[68:71], v[172:175], v[218:221], 0
	v_mfma_f32_16x16x32_bf16 v[64:67], v[180:183], v[218:221], 0
	v_mfma_f32_16x16x32_bf16 v[116:119], v[176:179], v[192:195], v[116:119]
	v_mfma_f32_16x16x32_bf16 v[112:115], v[184:187], v[192:195], v[112:115]
	v_mfma_f32_16x16x32_bf16 v[100:103], v[176:179], v[206:209], v[100:103]
	v_mfma_f32_16x16x32_bf16 v[96:99], v[184:187], v[206:209], v[96:99]
	v_mfma_f32_16x16x32_bf16 v[84:87], v[176:179], v[214:217], v[84:87]
	v_mfma_f32_16x16x32_bf16 v[80:83], v[184:187], v[214:217], v[80:83]
	v_mfma_f32_16x16x32_bf16 v[68:71], v[176:179], v[222:225], v[68:71]
	v_mfma_f32_16x16x32_bf16 v[64:67], v[184:187], v[222:225], v[64:67]
	s_setprio 0
	s_barrier
	s_add_i32 s93, s75, s14
	v_lshl_add_u64 v[226:227], s[48:49], 0, v[132:133]
	s_mov_b32 m0, s93
	ds_read_b128 v[188:191], v157 offset:16384
	ds_read_b128 v[192:195], v157 offset:17408
	ds_read_b128 v[202:205], v157 offset:18432
	ds_read_b128 v[206:209], v157 offset:19456
	ds_read_b128 v[210:213], v157 offset:20480
	ds_read_b128 v[214:217], v157 offset:21504
	ds_read_b128 v[218:221], v157 offset:22528
	ds_read_b128 v[222:225], v157 offset:23552
	global_load_lds_dwordx4 v[226:227], off
	s_add_i32 m0, s93, 0x2000
	v_lshl_add_u64 v[228:229], s[48:49], 0, v[128:129]
	s_add_u32 s48, s48, s10
	s_addc_u32 s49, s49, s11
	s_add_i32 s93, s77, s14
	global_load_lds_dwordx4 v[228:229], off
	v_lshl_add_u64 v[230:231], s[48:49], 0, v[132:133]
	s_mov_b32 m0, s93
	v_lshl_add_u64 v[232:233], s[48:49], 0, v[128:129]
	global_load_lds_dwordx4 v[230:231], off
	s_add_i32 m0, s93, 0x2000
	v_lshl_add_u64 v[234:235], s[88:89], 0, v[134:135]
	global_load_lds_dwordx4 v[232:233], off
	s_mov_b32 m0, s52
	v_lshl_add_u64 v[236:237], s[88:89], 0, v[130:131]
	global_load_lds_dwordx4 v[234:235], off
	s_mov_b32 m0, s53
	s_nop 0
	global_load_lds_dwordx4 v[236:237], off
	s_waitcnt vmcnt(8)
	s_waitcnt lgkmcnt(0)
	s_barrier
	s_setprio 1
	s_waitcnt lgkmcnt(0)
	v_mfma_f32_16x16x32_bf16 v[60:63], v[148:151], v[188:191], 0
	v_mfma_f32_16x16x32_bf16 v[56:59], v[164:167], v[188:191], 0
	v_mfma_f32_16x16x32_bf16 v[44:47], v[148:151], v[202:205], 0
	v_mfma_f32_16x16x32_bf16 v[40:43], v[164:167], v[202:205], 0
	v_mfma_f32_16x16x32_bf16 v[28:31], v[148:151], v[210:213], 0
	v_mfma_f32_16x16x32_bf16 v[24:27], v[164:167], v[210:213], 0
	v_mfma_f32_16x16x32_bf16 v[12:15], v[148:151], v[218:221], 0
	v_mfma_f32_16x16x32_bf16 v[8:11], v[164:167], v[218:221], 0
	v_mfma_f32_16x16x32_bf16 v[60:63], v[160:163], v[192:195], v[60:63]
	v_mfma_f32_16x16x32_bf16 v[56:59], v[168:171], v[192:195], v[56:59]
	v_mfma_f32_16x16x32_bf16 v[44:47], v[160:163], v[206:209], v[44:47]
	v_mfma_f32_16x16x32_bf16 v[40:43], v[168:171], v[206:209], v[40:43]
	v_mfma_f32_16x16x32_bf16 v[28:31], v[160:163], v[214:217], v[28:31]
	v_mfma_f32_16x16x32_bf16 v[24:27], v[168:171], v[214:217], v[24:27]
	v_mfma_f32_16x16x32_bf16 v[12:15], v[160:163], v[222:225], v[12:15]
	v_mfma_f32_16x16x32_bf16 v[8:11], v[168:171], v[222:225], v[8:11]
	s_setprio 0
	s_setprio 1
	v_mfma_f32_16x16x32_bf16 v[52:55], v[172:175], v[188:191], 0
	v_mfma_f32_16x16x32_bf16 v[48:51], v[180:183], v[188:191], 0
	v_mfma_f32_16x16x32_bf16 v[36:39], v[172:175], v[202:205], 0
	v_mfma_f32_16x16x32_bf16 v[32:35], v[180:183], v[202:205], 0
	v_mfma_f32_16x16x32_bf16 v[20:23], v[172:175], v[210:213], 0
	v_mfma_f32_16x16x32_bf16 v[16:19], v[180:183], v[210:213], 0
	v_mfma_f32_16x16x32_bf16 v[4:7], v[172:175], v[218:221], 0
	v_mfma_f32_16x16x32_bf16 v[0:3], v[180:183], v[218:221], 0
	v_mfma_f32_16x16x32_bf16 v[52:55], v[176:179], v[192:195], v[52:55]
	v_mfma_f32_16x16x32_bf16 v[48:51], v[184:187], v[192:195], v[48:51]
	v_mfma_f32_16x16x32_bf16 v[36:39], v[176:179], v[206:209], v[36:39]
	v_mfma_f32_16x16x32_bf16 v[32:35], v[184:187], v[206:209], v[32:35]
	v_mfma_f32_16x16x32_bf16 v[20:23], v[176:179], v[214:217], v[20:23]
	v_mfma_f32_16x16x32_bf16 v[16:19], v[184:187], v[214:217], v[16:19]
	v_mfma_f32_16x16x32_bf16 v[4:7], v[176:179], v[222:225], v[4:7]
	v_mfma_f32_16x16x32_bf16 v[0:3], v[184:187], v[222:225], v[0:3]
	s_setprio 0
	s_barrier
	s_add_i32 s93, 0, 0x18000
	v_add_u32_e32 v136, s93, v152
	s_add_i32 s94, 0, 0x1c000
	ds_read_b128 v[148:151], v136
	ds_read_b128 v[160:163], v136 offset:1024
	ds_read_b128 v[164:167], v136 offset:2048
	ds_read_b128 v[168:171], v136 offset:3072
	v_add_u32_e32 v136, s94, v152
	ds_read_b128 v[172:175], v136
	ds_read_b128 v[176:179], v136 offset:1024
	ds_read_b128 v[180:183], v136 offset:2048
	ds_read_b128 v[184:187], v136 offset:3072
	s_add_u32 s48, s88, s10
	s_addc_u32 s49, s89, s11
	s_mov_b32 m0, s54
	v_lshl_add_u64 v[238:239], s[48:49], 0, v[134:135]
	ds_read_b128 v[188:191], v157 offset:32768
	ds_read_b128 v[192:195], v157 offset:33792
	ds_read_b128 v[202:205], v157 offset:34816
	ds_read_b128 v[206:209], v157 offset:35840
	ds_read_b128 v[210:213], v157 offset:36864
	ds_read_b128 v[214:217], v157 offset:37888
	ds_read_b128 v[218:221], v157 offset:38912
	ds_read_b128 v[222:225], v157 offset:39936
	global_load_lds_dwordx4 v[238:239], off
	v_lshl_add_u64 v[238:239], s[48:49], 0, v[130:131]
	s_mov_b32 m0, s55
	s_nop 0
	global_load_lds_dwordx4 v[238:239], off
	s_waitcnt vmcnt(8)
	s_waitcnt lgkmcnt(0)
	s_barrier
	s_setprio 1
	s_waitcnt lgkmcnt(0)
	v_mfma_f32_16x16x32_bf16 v[124:127], v[148:151], v[188:191], v[124:127]
	v_mfma_f32_16x16x32_bf16 v[120:123], v[164:167], v[188:191], v[120:123]
	v_mfma_f32_16x16x32_bf16 v[108:111], v[148:151], v[202:205], v[108:111]
	v_mfma_f32_16x16x32_bf16 v[104:107], v[164:167], v[202:205], v[104:107]
	v_mfma_f32_16x16x32_bf16 v[92:95], v[148:151], v[210:213], v[92:95]
	v_mfma_f32_16x16x32_bf16 v[88:91], v[164:167], v[210:213], v[88:91]
	v_mfma_f32_16x16x32_bf16 v[76:79], v[148:151], v[218:221], v[76:79]
	v_mfma_f32_16x16x32_bf16 v[72:75], v[164:167], v[218:221], v[72:75]
	v_mfma_f32_16x16x32_bf16 v[124:127], v[160:163], v[192:195], v[124:127]
	v_mfma_f32_16x16x32_bf16 v[120:123], v[168:171], v[192:195], v[120:123]
	v_mfma_f32_16x16x32_bf16 v[108:111], v[160:163], v[206:209], v[108:111]
	v_mfma_f32_16x16x32_bf16 v[104:107], v[168:171], v[206:209], v[104:107]
	v_mfma_f32_16x16x32_bf16 v[92:95], v[160:163], v[214:217], v[92:95]
	v_mfma_f32_16x16x32_bf16 v[88:91], v[168:171], v[214:217], v[88:91]
	v_mfma_f32_16x16x32_bf16 v[76:79], v[160:163], v[222:225], v[76:79]
	v_mfma_f32_16x16x32_bf16 v[72:75], v[168:171], v[222:225], v[72:75]
	s_setprio 0
	s_setprio 1
	v_mfma_f32_16x16x32_bf16 v[116:119], v[172:175], v[188:191], v[116:119]
	v_mfma_f32_16x16x32_bf16 v[112:115], v[180:183], v[188:191], v[112:115]
	v_mfma_f32_16x16x32_bf16 v[100:103], v[172:175], v[202:205], v[100:103]
	v_mfma_f32_16x16x32_bf16 v[96:99], v[180:183], v[202:205], v[96:99]
	v_mfma_f32_16x16x32_bf16 v[84:87], v[172:175], v[210:213], v[84:87]
	v_mfma_f32_16x16x32_bf16 v[80:83], v[180:183], v[210:213], v[80:83]
	v_mfma_f32_16x16x32_bf16 v[68:71], v[172:175], v[218:221], v[68:71]
	v_mfma_f32_16x16x32_bf16 v[64:67], v[180:183], v[218:221], v[64:67]
	v_mfma_f32_16x16x32_bf16 v[116:119], v[176:179], v[192:195], v[116:119]
	v_mfma_f32_16x16x32_bf16 v[112:115], v[184:187], v[192:195], v[112:115]
	v_mfma_f32_16x16x32_bf16 v[100:103], v[176:179], v[206:209], v[100:103]
	v_mfma_f32_16x16x32_bf16 v[96:99], v[184:187], v[206:209], v[96:99]
	v_mfma_f32_16x16x32_bf16 v[84:87], v[176:179], v[214:217], v[84:87]
	v_mfma_f32_16x16x32_bf16 v[80:83], v[184:187], v[214:217], v[80:83]
	v_mfma_f32_16x16x32_bf16 v[68:71], v[176:179], v[222:225], v[68:71]
	v_mfma_f32_16x16x32_bf16 v[64:67], v[184:187], v[222:225], v[64:67]
	s_setprio 0
	s_barrier
	s_add_i32 s48, s93, s14
	v_lshl_add_u64 v[226:227], v[226:227], 0, s[66:67]
	s_mov_b32 m0, s48
	ds_read_b128 v[188:191], v157 offset:49152
	ds_read_b128 v[192:195], v157 offset:50176
	ds_read_b128 v[202:205], v157 offset:51200
	ds_read_b128 v[206:209], v157 offset:52224
	ds_read_b128 v[210:213], v157 offset:53248
	ds_read_b128 v[214:217], v157 offset:54272
	ds_read_b128 v[218:221], v157 offset:55296
	ds_read_b128 v[222:225], v157 offset:56320
	global_load_lds_dwordx4 v[226:227], off
	v_lshl_add_u64 v[226:227], v[228:229], 0, s[66:67]
	s_add_i32 m0, s48, 0x2000
	s_add_i32 s48, s94, s14
	global_load_lds_dwordx4 v[226:227], off
	v_lshl_add_u64 v[226:227], v[230:231], 0, s[66:67]
	s_mov_b32 m0, s48
	s_nop 0
	global_load_lds_dwordx4 v[226:227], off
	v_lshl_add_u64 v[226:227], v[232:233], 0, s[66:67]
	s_add_i32 m0, s48, 0x2000
	s_nop 0
	global_load_lds_dwordx4 v[226:227], off
	v_lshl_add_u64 v[226:227], v[234:235], 0, s[66:67]
	s_mov_b32 m0, s70
	s_nop 0
	global_load_lds_dwordx4 v[226:227], off
	v_lshl_add_u64 v[226:227], v[236:237], 0, s[66:67]
	s_mov_b32 m0, s71
	s_nop 0
	global_load_lds_dwordx4 v[226:227], off
	s_waitcnt vmcnt(8)
	s_waitcnt lgkmcnt(0)
	s_barrier
	s_setprio 1
	s_waitcnt lgkmcnt(0)
	v_mfma_f32_16x16x32_bf16 v[60:63], v[148:151], v[188:191], v[60:63]
	v_mfma_f32_16x16x32_bf16 v[56:59], v[164:167], v[188:191], v[56:59]
	v_mfma_f32_16x16x32_bf16 v[44:47], v[148:151], v[202:205], v[44:47]
	v_mfma_f32_16x16x32_bf16 v[40:43], v[164:167], v[202:205], v[40:43]
	v_mfma_f32_16x16x32_bf16 v[28:31], v[148:151], v[210:213], v[28:31]
	v_mfma_f32_16x16x32_bf16 v[24:27], v[164:167], v[210:213], v[24:27]
	v_mfma_f32_16x16x32_bf16 v[12:15], v[148:151], v[218:221], v[12:15]
	v_mfma_f32_16x16x32_bf16 v[8:11], v[164:167], v[218:221], v[8:11]
	v_mfma_f32_16x16x32_bf16 v[60:63], v[160:163], v[192:195], v[60:63]
	v_mfma_f32_16x16x32_bf16 v[56:59], v[168:171], v[192:195], v[56:59]
	v_mfma_f32_16x16x32_bf16 v[44:47], v[160:163], v[206:209], v[44:47]
	v_mfma_f32_16x16x32_bf16 v[40:43], v[168:171], v[206:209], v[40:43]
	v_mfma_f32_16x16x32_bf16 v[28:31], v[160:163], v[214:217], v[28:31]
	v_mfma_f32_16x16x32_bf16 v[24:27], v[168:171], v[214:217], v[24:27]
	v_mfma_f32_16x16x32_bf16 v[12:15], v[160:163], v[222:225], v[12:15]
	v_mfma_f32_16x16x32_bf16 v[8:11], v[168:171], v[222:225], v[8:11]
	s_setprio 0
	s_setprio 1
	v_mfma_f32_16x16x32_bf16 v[52:55], v[172:175], v[188:191], v[52:55]
	v_mfma_f32_16x16x32_bf16 v[48:51], v[180:183], v[188:191], v[48:51]
	v_mfma_f32_16x16x32_bf16 v[36:39], v[172:175], v[202:205], v[36:39]
	v_mfma_f32_16x16x32_bf16 v[32:35], v[180:183], v[202:205], v[32:35]
	v_mfma_f32_16x16x32_bf16 v[20:23], v[172:175], v[210:213], v[20:23]
	v_mfma_f32_16x16x32_bf16 v[16:19], v[180:183], v[210:213], v[16:19]
	v_mfma_f32_16x16x32_bf16 v[4:7], v[172:175], v[218:221], v[4:7]
	v_mfma_f32_16x16x32_bf16 v[0:3], v[180:183], v[218:221], v[0:3]
	v_mfma_f32_16x16x32_bf16 v[52:55], v[176:179], v[192:195], v[52:55]
	v_mfma_f32_16x16x32_bf16 v[48:51], v[184:187], v[192:195], v[48:51]
	v_mfma_f32_16x16x32_bf16 v[36:39], v[176:179], v[206:209], v[36:39]
	v_mfma_f32_16x16x32_bf16 v[32:35], v[184:187], v[206:209], v[32:35]
	v_mfma_f32_16x16x32_bf16 v[20:23], v[176:179], v[214:217], v[20:23]
	v_mfma_f32_16x16x32_bf16 v[16:19], v[184:187], v[214:217], v[16:19]
	v_mfma_f32_16x16x32_bf16 v[4:7], v[176:179], v[222:225], v[4:7]
	v_mfma_f32_16x16x32_bf16 v[0:3], v[184:187], v[222:225], v[0:3]
	s_setprio 0
	s_barrier
	s_add_u32 s86, s86, 0x100
	s_addc_u32 s87, s87, 0
	s_add_u32 s90, s90, 0x100
	s_addc_u32 s91, s91, 0
	s_cmp_ge_i32 s92, s64
	s_mov_b32 s88, s92

.LBB0_1202:
	s_add_u32 s48, s18, 0x100
	s_addc_u32 s49, s19, 0
	s_mov_b32 s50, -2
	ds_read_b128 v[144:147], v153
	ds_read_b128 v[156:159], v153 offset:1024
	ds_read_b128 v[160:163], v153 offset:2048
	ds_read_b128 v[164:167], v153 offset:3072
	ds_read_b128 v[168:171], v154
	ds_read_b128 v[172:175], v154 offset:1024
	ds_read_b128 v[176:179], v154 offset:2048
	ds_read_b128 v[180:183], v154 offset:3072
	s_add_u32 s18, s16, 0x100
	s_addc_u32 s19, s17, 0
	s_cmp_eq_u32 s50, 40
	s_cselect_b32 s23, s5, s19
	s_cselect_b32 s22, s4, s18
	s_cselect_b32 s21, s15, s49
	s_cselect_b32 s20, s14, s48
	v_lshl_add_u64 v[148:149], s[16:17], 0, v[136:137]
	s_add_i32 m0, s24, 0xc000
	ds_read_b128 v[184:187], v155
	ds_read_b128 v[188:191], v155 offset:1024
	ds_read_b128 v[192:195], v155 offset:2048
	ds_read_b128 v[196:199], v155 offset:3072
	ds_read_b128 v[200:203], v155 offset:4096
	ds_read_b128 v[204:207], v155 offset:5120
	ds_read_b128 v[208:211], v155 offset:6144
	ds_read_b128 v[212:215], v155 offset:7168
	global_load_lds_dwordx4 v[148:149], off
	v_lshl_add_u64 v[148:149], s[16:17], 0, v[138:139]
	s_add_i32 m0, s24, 0xe000
	s_nop 0
	global_load_lds_dwordx4 v[148:149], off
	s_waitcnt vmcnt(8)
	s_waitcnt lgkmcnt(0)
	s_barrier
	s_setprio 1
	s_waitcnt lgkmcnt(0)
	v_mfma_f32_16x16x32_bf16 v[124:127], v[144:147], v[184:187], 0
	v_mfma_f32_16x16x32_bf16 v[120:123], v[160:163], v[184:187], 0
	v_mfma_f32_16x16x32_bf16 v[108:111], v[144:147], v[192:195], 0
	v_mfma_f32_16x16x32_bf16 v[104:107], v[160:163], v[192:195], 0
	v_mfma_f32_16x16x32_bf16 v[92:95], v[144:147], v[200:203], 0
	v_mfma_f32_16x16x32_bf16 v[88:91], v[160:163], v[200:203], 0
	v_mfma_f32_16x16x32_bf16 v[76:79], v[144:147], v[208:211], 0
	v_mfma_f32_16x16x32_bf16 v[72:75], v[160:163], v[208:211], 0
	v_mfma_f32_16x16x32_bf16 v[124:127], v[156:159], v[188:191], v[124:127]
	v_mfma_f32_16x16x32_bf16 v[120:123], v[164:167], v[188:191], v[120:123]
	v_mfma_f32_16x16x32_bf16 v[108:111], v[156:159], v[196:199], v[108:111]
	v_mfma_f32_16x16x32_bf16 v[104:107], v[164:167], v[196:199], v[104:107]
	v_mfma_f32_16x16x32_bf16 v[92:95], v[156:159], v[204:207], v[92:95]
	v_mfma_f32_16x16x32_bf16 v[88:91], v[164:167], v[204:207], v[88:91]
	v_mfma_f32_16x16x32_bf16 v[76:79], v[156:159], v[212:215], v[76:79]
	v_mfma_f32_16x16x32_bf16 v[72:75], v[164:167], v[212:215], v[72:75]
	s_setprio 0
	s_setprio 1
	v_mfma_f32_16x16x32_bf16 v[116:119], v[168:171], v[184:187], 0
	v_mfma_f32_16x16x32_bf16 v[112:115], v[176:179], v[184:187], 0
	v_mfma_f32_16x16x32_bf16 v[100:103], v[168:171], v[192:195], 0
	v_mfma_f32_16x16x32_bf16 v[96:99], v[176:179], v[192:195], 0
	v_mfma_f32_16x16x32_bf16 v[84:87], v[168:171], v[200:203], 0
	v_mfma_f32_16x16x32_bf16 v[80:83], v[176:179], v[200:203], 0
	v_mfma_f32_16x16x32_bf16 v[68:71], v[168:171], v[208:211], 0
	v_mfma_f32_16x16x32_bf16 v[64:67], v[176:179], v[208:211], 0
	v_mfma_f32_16x16x32_bf16 v[116:119], v[172:175], v[188:191], v[116:119]
	v_mfma_f32_16x16x32_bf16 v[112:115], v[180:183], v[188:191], v[112:115]
	v_mfma_f32_16x16x32_bf16 v[100:103], v[172:175], v[196:199], v[100:103]
	v_mfma_f32_16x16x32_bf16 v[96:99], v[180:183], v[196:199], v[96:99]
	v_mfma_f32_16x16x32_bf16 v[84:87], v[172:175], v[204:207], v[84:87]
	v_mfma_f32_16x16x32_bf16 v[80:83], v[180:183], v[204:207], v[80:83]
	v_mfma_f32_16x16x32_bf16 v[68:71], v[172:175], v[212:215], v[68:71]
	v_mfma_f32_16x16x32_bf16 v[64:67], v[180:183], v[212:215], v[64:67]
	s_setprio 0
	s_barrier
	s_add_i32 s16, s42, s3
	v_lshl_add_u64 v[148:149], s[20:21], 0, v[130:131]
	s_mov_b32 m0, s16
	ds_read_b128 v[184:187], v155 offset:16384
	ds_read_b128 v[188:191], v155 offset:17408
	ds_read_b128 v[192:195], v155 offset:18432
	ds_read_b128 v[196:199], v155 offset:19456
	ds_read_b128 v[200:203], v155 offset:20480
	ds_read_b128 v[204:207], v155 offset:21504
	ds_read_b128 v[208:211], v155 offset:22528
	ds_read_b128 v[212:215], v155 offset:23552
	global_load_lds_dwordx4 v[148:149], off
	s_add_i32 m0, s16, 0x2000
	s_add_u32 s16, s20, 0xb0000
	v_lshl_add_u64 v[216:217], s[20:21], 0, v[134:135]
	s_addc_u32 s17, s21, 0
	s_add_i32 s51, s43, s3
	global_load_lds_dwordx4 v[216:217], off
	v_lshl_add_u64 v[218:219], s[16:17], 0, v[130:131]
	s_mov_b32 m0, s51
	v_lshl_add_u64 v[220:221], s[22:23], 0, v[132:133]
	global_load_lds_dwordx4 v[218:219], off
	v_lshl_add_u64 v[218:219], s[16:17], 0, v[134:135]
	s_add_i32 m0, s51, 0x2000
	s_nop 0
	global_load_lds_dwordx4 v[218:219], off
	v_lshl_add_u64 v[218:219], s[22:23], 0, v[128:129]
	s_mov_b32 m0, s24
	s_nop 0
	global_load_lds_dwordx4 v[218:219], off
	s_mov_b32 m0, s25
	s_nop 0
	global_load_lds_dwordx4 v[220:221], off
	s_waitcnt vmcnt(8)
	s_waitcnt lgkmcnt(0)
	s_barrier
	s_setprio 1
	s_waitcnt lgkmcnt(0)
	v_mfma_f32_16x16x32_bf16 v[60:63], v[144:147], v[184:187], 0
	v_mfma_f32_16x16x32_bf16 v[56:59], v[160:163], v[184:187], 0
	v_mfma_f32_16x16x32_bf16 v[44:47], v[144:147], v[192:195], 0
	v_mfma_f32_16x16x32_bf16 v[40:43], v[160:163], v[192:195], 0
	v_mfma_f32_16x16x32_bf16 v[28:31], v[144:147], v[200:203], 0
	v_mfma_f32_16x16x32_bf16 v[24:27], v[160:163], v[200:203], 0
	v_mfma_f32_16x16x32_bf16 v[12:15], v[144:147], v[208:211], 0
	v_mfma_f32_16x16x32_bf16 v[8:11], v[160:163], v[208:211], 0
	v_mfma_f32_16x16x32_bf16 v[60:63], v[156:159], v[188:191], v[60:63]
	v_mfma_f32_16x16x32_bf16 v[56:59], v[164:167], v[188:191], v[56:59]
	v_mfma_f32_16x16x32_bf16 v[44:47], v[156:159], v[196:199], v[44:47]
	v_mfma_f32_16x16x32_bf16 v[40:43], v[164:167], v[196:199], v[40:43]
	v_mfma_f32_16x16x32_bf16 v[28:31], v[156:159], v[204:207], v[28:31]
	v_mfma_f32_16x16x32_bf16 v[24:27], v[164:167], v[204:207], v[24:27]
	v_mfma_f32_16x16x32_bf16 v[12:15], v[156:159], v[212:215], v[12:15]
	v_mfma_f32_16x16x32_bf16 v[8:11], v[164:167], v[212:215], v[8:11]
	s_setprio 0
	s_setprio 1
	v_mfma_f32_16x16x32_bf16 v[52:55], v[168:171], v[184:187], 0
	v_mfma_f32_16x16x32_bf16 v[48:51], v[176:179], v[184:187], 0
	v_mfma_f32_16x16x32_bf16 v[36:39], v[168:171], v[192:195], 0
	v_mfma_f32_16x16x32_bf16 v[32:35], v[176:179], v[192:195], 0
	v_mfma_f32_16x16x32_bf16 v[20:23], v[168:171], v[200:203], 0
	v_mfma_f32_16x16x32_bf16 v[16:19], v[176:179], v[200:203], 0
	v_mfma_f32_16x16x32_bf16 v[4:7], v[168:171], v[208:211], 0
	v_mfma_f32_16x16x32_bf16 v[0:3], v[176:179], v[208:211], 0
	v_mfma_f32_16x16x32_bf16 v[52:55], v[172:175], v[188:191], v[52:55]
	v_mfma_f32_16x16x32_bf16 v[48:51], v[180:183], v[188:191], v[48:51]
	v_mfma_f32_16x16x32_bf16 v[36:39], v[172:175], v[196:199], v[36:39]
	v_mfma_f32_16x16x32_bf16 v[32:35], v[180:183], v[196:199], v[32:35]
	v_mfma_f32_16x16x32_bf16 v[20:23], v[172:175], v[204:207], v[20:23]
	v_mfma_f32_16x16x32_bf16 v[16:19], v[180:183], v[204:207], v[16:19]
	v_mfma_f32_16x16x32_bf16 v[4:7], v[172:175], v[212:215], v[4:7]
	v_mfma_f32_16x16x32_bf16 v[0:3], v[180:183], v[212:215], v[0:3]
	s_setprio 0
	s_barrier
	s_add_i32 s51, 0, 0x18000
	s_add_i32 s52, 0, 0x1c000
	v_add_u32_e32 v164, s51, v151
	v_add_u32_e32 v180, s52, v151
	ds_read_b128 v[144:147], v164
	ds_read_b128 v[156:159], v164 offset:1024
	ds_read_b128 v[160:163], v164 offset:2048
	ds_read_b128 v[164:167], v164 offset:3072
	ds_read_b128 v[168:171], v180
	ds_read_b128 v[172:175], v180 offset:1024
	ds_read_b128 v[176:179], v180 offset:2048
	ds_read_b128 v[180:183], v180 offset:3072
	s_add_u32 s16, s22, 0xb0000
	s_addc_u32 s17, s23, 0
	s_mov_b32 m0, s26
	v_lshl_add_u64 v[222:223], s[16:17], 0, v[128:129]
	ds_read_b128 v[184:187], v155 offset:32768
	ds_read_b128 v[188:191], v155 offset:33792
	ds_read_b128 v[192:195], v155 offset:34816
	ds_read_b128 v[196:199], v155 offset:35840
	ds_read_b128 v[200:203], v155 offset:36864
	ds_read_b128 v[204:207], v155 offset:37888
	ds_read_b128 v[208:211], v155 offset:38912
	ds_read_b128 v[212:215], v155 offset:39936
	global_load_lds_dwordx4 v[222:223], off
	v_lshl_add_u64 v[222:223], s[16:17], 0, v[132:133]
	s_mov_b32 m0, s27
	s_nop 0
	global_load_lds_dwordx4 v[222:223], off
	s_waitcnt vmcnt(8)
	s_waitcnt lgkmcnt(0)
	s_barrier
	s_setprio 1
	s_waitcnt lgkmcnt(0)
	v_mfma_f32_16x16x32_bf16 v[124:127], v[144:147], v[184:187], v[124:127]
	v_mfma_f32_16x16x32_bf16 v[120:123], v[160:163], v[184:187], v[120:123]
	v_mfma_f32_16x16x32_bf16 v[108:111], v[144:147], v[192:195], v[108:111]
	v_mfma_f32_16x16x32_bf16 v[104:107], v[160:163], v[192:195], v[104:107]
	v_mfma_f32_16x16x32_bf16 v[92:95], v[144:147], v[200:203], v[92:95]
	v_mfma_f32_16x16x32_bf16 v[88:91], v[160:163], v[200:203], v[88:91]
	v_mfma_f32_16x16x32_bf16 v[76:79], v[144:147], v[208:211], v[76:79]
	v_mfma_f32_16x16x32_bf16 v[72:75], v[160:163], v[208:211], v[72:75]
	v_mfma_f32_16x16x32_bf16 v[124:127], v[156:159], v[188:191], v[124:127]
	v_mfma_f32_16x16x32_bf16 v[120:123], v[164:167], v[188:191], v[120:123]
	v_mfma_f32_16x16x32_bf16 v[108:111], v[156:159], v[196:199], v[108:111]
	v_mfma_f32_16x16x32_bf16 v[104:107], v[164:167], v[196:199], v[104:107]
	v_mfma_f32_16x16x32_bf16 v[92:95], v[156:159], v[204:207], v[92:95]
	v_mfma_f32_16x16x32_bf16 v[88:91], v[164:167], v[204:207], v[88:91]
	v_mfma_f32_16x16x32_bf16 v[76:79], v[156:159], v[212:215], v[76:79]
	v_mfma_f32_16x16x32_bf16 v[72:75], v[164:167], v[212:215], v[72:75]
	s_setprio 0
	s_setprio 1
	v_mfma_f32_16x16x32_bf16 v[116:119], v[168:171], v[184:187], v[116:119]
	v_mfma_f32_16x16x32_bf16 v[112:115], v[176:179], v[184:187], v[112:115]
	v_mfma_f32_16x16x32_bf16 v[100:103], v[168:171], v[192:195], v[100:103]
	v_mfma_f32_16x16x32_bf16 v[96:99], v[176:179], v[192:195], v[96:99]
	v_mfma_f32_16x16x32_bf16 v[84:87], v[168:171], v[200:203], v[84:87]
	v_mfma_f32_16x16x32_bf16 v[80:83], v[176:179], v[200:203], v[80:83]
	v_mfma_f32_16x16x32_bf16 v[68:71], v[168:171], v[208:211], v[68:71]
	v_mfma_f32_16x16x32_bf16 v[64:67], v[176:179], v[208:211], v[64:67]
	v_mfma_f32_16x16x32_bf16 v[116:119], v[172:175], v[188:191], v[116:119]
	v_mfma_f32_16x16x32_bf16 v[112:115], v[180:183], v[188:191], v[112:115]
	v_mfma_f32_16x16x32_bf16 v[100:103], v[172:175], v[196:199], v[100:103]
	v_mfma_f32_16x16x32_bf16 v[96:99], v[180:183], v[196:199], v[96:99]
	v_mfma_f32_16x16x32_bf16 v[84:87], v[172:175], v[204:207], v[84:87]
	v_mfma_f32_16x16x32_bf16 v[80:83], v[180:183], v[204:207], v[80:83]
	v_mfma_f32_16x16x32_bf16 v[68:71], v[172:175], v[212:215], v[68:71]
	v_mfma_f32_16x16x32_bf16 v[64:67], v[180:183], v[212:215], v[64:67]
	s_setprio 0
	s_barrier
	s_add_i32 s16, s51, s3
	v_lshl_add_u64 v[148:149], v[148:149], 0, s[10:11]
	s_mov_b32 m0, s16
	ds_read_b128 v[184:187], v155 offset:49152
	ds_read_b128 v[188:191], v155 offset:50176
	ds_read_b128 v[192:195], v155 offset:51200
	ds_read_b128 v[196:199], v155 offset:52224
	ds_read_b128 v[200:203], v155 offset:53248
	ds_read_b128 v[204:207], v155 offset:54272
	ds_read_b128 v[208:211], v155 offset:55296
	ds_read_b128 v[212:215], v155 offset:56320
	global_load_lds_dwordx4 v[148:149], off
	s_add_i32 m0, s16, 0x2000
	s_add_u32 s16, s20, 0xb0080
	v_lshl_add_u64 v[148:149], v[216:217], 0, s[10:11]
	s_addc_u32 s17, s21, 0
	s_add_i32 s20, s52, s3
	global_load_lds_dwordx4 v[148:149], off
	v_lshl_add_u64 v[148:149], s[16:17], 0, v[130:131]
	s_mov_b32 m0, s20
	s_nop 0
	global_load_lds_dwordx4 v[148:149], off
	v_lshl_add_u64 v[148:149], s[16:17], 0, v[134:135]
	s_add_i32 m0, s20, 0x2000
	s_nop 0
	global_load_lds_dwordx4 v[148:149], off
	v_lshl_add_u64 v[148:149], v[218:219], 0, s[10:11]
	s_mov_b32 m0, s37
	s_nop 0
	global_load_lds_dwordx4 v[148:149], off
	v_lshl_add_u64 v[148:149], v[220:221], 0, s[10:11]
	s_mov_b32 m0, s40
	s_nop 0
	global_load_lds_dwordx4 v[148:149], off
	s_waitcnt vmcnt(8)
	s_waitcnt lgkmcnt(0)
	s_barrier
	s_setprio 1
	s_waitcnt lgkmcnt(0)
	v_mfma_f32_16x16x32_bf16 v[60:63], v[144:147], v[184:187], v[60:63]
	v_mfma_f32_16x16x32_bf16 v[56:59], v[160:163], v[184:187], v[56:59]
	v_mfma_f32_16x16x32_bf16 v[44:47], v[144:147], v[192:195], v[44:47]
	v_mfma_f32_16x16x32_bf16 v[40:43], v[160:163], v[192:195], v[40:43]
	v_mfma_f32_16x16x32_bf16 v[28:31], v[144:147], v[200:203], v[28:31]
	v_mfma_f32_16x16x32_bf16 v[24:27], v[160:163], v[200:203], v[24:27]
	v_mfma_f32_16x16x32_bf16 v[12:15], v[144:147], v[208:211], v[12:15]
	v_mfma_f32_16x16x32_bf16 v[8:11], v[160:163], v[208:211], v[8:11]
	v_mfma_f32_16x16x32_bf16 v[60:63], v[156:159], v[188:191], v[60:63]
	v_mfma_f32_16x16x32_bf16 v[56:59], v[164:167], v[188:191], v[56:59]
	v_mfma_f32_16x16x32_bf16 v[44:47], v[156:159], v[196:199], v[44:47]
	v_mfma_f32_16x16x32_bf16 v[40:43], v[164:167], v[196:199], v[40:43]
	v_mfma_f32_16x16x32_bf16 v[28:31], v[156:159], v[204:207], v[28:31]
	v_mfma_f32_16x16x32_bf16 v[24:27], v[164:167], v[204:207], v[24:27]
	v_mfma_f32_16x16x32_bf16 v[12:15], v[156:159], v[212:215], v[12:15]
	v_mfma_f32_16x16x32_bf16 v[8:11], v[164:167], v[212:215], v[8:11]
	s_setprio 0
	s_setprio 1
	v_mfma_f32_16x16x32_bf16 v[52:55], v[168:171], v[184:187], v[52:55]
	v_mfma_f32_16x16x32_bf16 v[48:51], v[176:179], v[184:187], v[48:51]
	v_mfma_f32_16x16x32_bf16 v[36:39], v[168:171], v[192:195], v[36:39]
	v_mfma_f32_16x16x32_bf16 v[32:35], v[176:179], v[192:195], v[32:35]
	v_mfma_f32_16x16x32_bf16 v[20:23], v[168:171], v[200:203], v[20:23]
	v_mfma_f32_16x16x32_bf16 v[16:19], v[176:179], v[200:203], v[16:19]
	v_mfma_f32_16x16x32_bf16 v[4:7], v[168:171], v[208:211], v[4:7]
	v_mfma_f32_16x16x32_bf16 v[0:3], v[176:179], v[208:211], v[0:3]
	v_mfma_f32_16x16x32_bf16 v[52:55], v[172:175], v[188:191], v[52:55]
	v_mfma_f32_16x16x32_bf16 v[48:51], v[180:183], v[188:191], v[48:51]
	v_mfma_f32_16x16x32_bf16 v[36:39], v[172:175], v[196:199], v[36:39]
	v_mfma_f32_16x16x32_bf16 v[32:35], v[180:183], v[196:199], v[32:35]
	v_mfma_f32_16x16x32_bf16 v[20:23], v[172:175], v[204:207], v[20:23]
	v_mfma_f32_16x16x32_bf16 v[16:19], v[180:183], v[204:207], v[16:19]
	v_mfma_f32_16x16x32_bf16 v[4:7], v[172:175], v[212:215], v[4:7]
	v_mfma_f32_16x16x32_bf16 v[0:3], v[180:183], v[212:215], v[0:3]
	s_setprio 0
	s_barrier
	s_add_i32 s50, s50, 2
	s_add_u32 s48, s48, 0x100
	s_addc_u32 s49, s49, 0
	s_cmp_gt_u32 s50, 41
	s_mov_b64 s[16:17], s[18:19]
